# GEMM K-loops: s_setprio 0 issued before parking at the pre-MMA barrier, so the MFMA segment starts with one instruction less after release
# baseline (speedup 1.0000x reference)
; #define PG8_STAGE(bufoff, gbase, voff) do { _Pragma("unroll") for (int _i = 0; _i < 2; ++_i) \
;         __builtin_amdgcn_global_load_lds((const unsigned*)((const char*)(gbase) + (voff)[_i]), (LAS unsigned*)(lds + (bufoff) + ldsw + _i * 8192), 16, 0, 0); } while (0)
; #define PG8_LDA(dst, b, h) do { _Pragma("unroll") for (int m = 0; m < 4; ++m) _Pragma("unroll") for (int k = 0; k < 2; ++k) dst[m][k] = *(const LAS bf16x8*)(lds + PG8_SA(b, h) + aoff + m * 2048 + k * 1024); } while (0)
; #define PG8_LDB(dst, b, h) do { _Pragma("unroll") for (int n = 0; n < 2; ++n) _Pragma("unroll") for (int k = 0; k < 2; ++k) dst[n][k] = *(const LAS bf16x8*)(lds + PG8_SB(b, h) + boff + n * 2048 + k * 1024); } while (0)
; #define PG8_WAIT_V(n) asm volatile("s_waitcnt vmcnt(" #n ")" ::: "memory")
; #define PG8_WAIT_L(n) asm volatile("s_waitcnt lgkmcnt(" #n ")" ::: "memory")
; #define PG8_BAR __builtin_amdgcn_s_barrier()
; #define PG8_SCHED __builtin_amdgcn_sched_barrier(0)
; template <class Epi, class Sched, int LD>
; __device__ __forceinline__ void gemm_phase(LAS unsigned char* lds, const Gemm g, const Sched& S, const Epi& E) {
;     ...
;         for (int t = 0; t < nt; t += 2) {
;             const bool last = (t == nt - 2);
;             const char* a1 = cA + (size_t)(t + 1) * kstep;
;             const char* a2 = last ? nA : cA + (size_t)(t + 2) * kstep; const char* b2 = last ? nB : cB + (size_t)(t + 2) * kstep;
;             const char* a3 = a2 + kstep; const char* b3 = b2 + kstep;
;             PG8_LDB(B0, 0, 0); PG8_SCHED; PG8_LDA(At, 0, 0); PG8_STAGE(PG8_SA(1, 1), a1 + hstep, voffA);
;             PG8_WAIT_L(8); PG8_BAR; PG8_WAIT_L(0); PG8_MMA(0, 0, At, B0); PG8_BAR; PG8_SCHED;
;             PG8_LDB(B1, 0, 1); PG8_STAGE(PG8_SB(0, 0), b2, voffB);
;             PG8_BAR; PG8_WAIT_L(0); PG8_MMA(0, 1, At, B1); PG8_BAR;
;             PG8_LDA(At, 0, 1); PG8_STAGE(PG8_SA(0, 0), a2, voffA);
;             PG8_BAR; PG8_WAIT_L(0); PG8_MMA(1, 0, At, B0); PG8_BAR; PG8_SCHED;
;             PG8_STAGE(PG8_SB(0, 1), b2 + hstep, voffB);
;             PG8_WAIT_V(6); PG8_BAR; PG8_MMA(1, 1, At, B1); PG8_BAR;
;             PG8_LDB(B0, 1, 0); PG8_SCHED; PG8_LDA(At, 1, 0); PG8_STAGE(PG8_SA(0, 1), a2 + hstep, voffA);
;             PG8_WAIT_L(8); PG8_BAR; PG8_WAIT_L(0); PG8_MMA(0, 0, At, B0); PG8_BAR; PG8_SCHED;
.LBB0_58:
	s_add_i32 s71, s4, 2
	s_add_u32 s48, s46, 0x4000
	s_addc_u32 s5, s47, 0
	s_cmp_eq_u32 s68, s4
	s_cselect_b32 s4, s42, s48
	s_cselect_b32 s5, s43, s5
	s_cselect_b32 s48, s44, s69
	s_cselect_b32 s49, s45, s70
	s_add_u32 s50, s4, 0x8000
	s_addc_u32 s51, s5, 0
	s_add_i32 s72, 0, 0x10000
	s_add_i32 m0, s39, 0xc000
	ds_read_b128 v[180:183], v148
	ds_read_b128 v[184:187], v148 offset:1024
	ds_read_b128 v[188:191], v148 offset:2048
	ds_read_b128 v[192:195], v148 offset:3072
	ds_read_b128 v[196:199], v148 offset:4096
	ds_read_b128 v[200:203], v148 offset:5120
	ds_read_b128 v[204:207], v148 offset:6144
	ds_read_b128 v[208:211], v148 offset:7168
	global_load_lds_dwordx4 v132, s[46:47]
	s_add_i32 m0, s39, 0xe000
	s_nop 0
	global_load_lds_dwordx4 v138, s[46:47]
	s_waitcnt lgkmcnt(8)
	s_setprio 0
	s_barrier
	s_waitcnt lgkmcnt(0)
	v_mfma_f32_16x16x32_bf16 v[128:131], v[140:143], v[180:183], v[128:131]
	v_mfma_f32_16x16x32_bf16 v[124:127], v[154:157], v[180:183], v[124:127]
	v_mfma_f32_16x16x32_bf16 v[112:115], v[140:143], v[188:191], v[112:115]
	v_mfma_f32_16x16x32_bf16 v[108:111], v[154:157], v[188:191], v[108:111]
	v_mfma_f32_16x16x32_bf16 v[96:99], v[140:143], v[196:199], v[96:99]
	v_mfma_f32_16x16x32_bf16 v[92:95], v[154:157], v[196:199], v[92:95]
	v_mfma_f32_16x16x32_bf16 v[80:83], v[140:143], v[204:207], v[80:83]
	v_mfma_f32_16x16x32_bf16 v[76:79], v[154:157], v[204:207], v[76:79]
	v_mfma_f32_16x16x32_bf16 v[128:131], v[150:153], v[184:187], v[128:131]
	v_mfma_f32_16x16x32_bf16 v[124:127], v[176:179], v[184:187], v[124:127]
	v_mfma_f32_16x16x32_bf16 v[112:115], v[150:153], v[192:195], v[112:115]
	v_mfma_f32_16x16x32_bf16 v[108:111], v[176:179], v[192:195], v[108:111]
	v_mfma_f32_16x16x32_bf16 v[96:99], v[150:153], v[200:203], v[96:99]
	v_mfma_f32_16x16x32_bf16 v[92:95], v[176:179], v[200:203], v[92:95]
	s_barrier
	s_setprio 3
	v_mfma_f32_16x16x32_bf16 v[80:83], v[150:153], v[208:211], v[80:83]
	v_mfma_f32_16x16x32_bf16 v[76:79], v[176:179], v[208:211], v[76:79]
	s_setprio 2
	s_add_i32 s74, 0, 0x14000
	s_add_i32 s72, s72, s29
	ds_read_b128 v[212:215], v228 offset:16384
	ds_read_b128 v[216:219], v228 offset:17408
	ds_read_b128 v[220:223], v228 offset:18432
	ds_read_b128 v[224:227], v228 offset:19456
	s_mov_b32 m0, s72
	s_nop 0
	global_load_lds_dwordx4 v132, s[48:49]
	s_add_i32 m0, s72, 0x2000
	s_nop 0
	global_load_lds_dwordx4 v138, s[48:49]
	s_setprio 0
	s_barrier
	s_waitcnt lgkmcnt(0)
	v_mfma_f32_16x16x32_bf16 v[120:123], v[212:215], v[180:183], v[120:123]
	v_mfma_f32_16x16x32_bf16 v[116:119], v[220:223], v[180:183], v[116:119]
	v_mfma_f32_16x16x32_bf16 v[104:107], v[212:215], v[188:191], v[104:107]
	v_mfma_f32_16x16x32_bf16 v[100:103], v[220:223], v[188:191], v[100:103]
	v_mfma_f32_16x16x32_bf16 v[88:91], v[212:215], v[196:199], v[88:91]
	v_mfma_f32_16x16x32_bf16 v[84:87], v[220:223], v[196:199], v[84:87]
	v_mfma_f32_16x16x32_bf16 v[72:75], v[212:215], v[204:207], v[72:75]
	v_mfma_f32_16x16x32_bf16 v[68:71], v[220:223], v[204:207], v[68:71]
	v_mfma_f32_16x16x32_bf16 v[120:123], v[216:219], v[184:187], v[120:123]
	v_mfma_f32_16x16x32_bf16 v[116:119], v[224:227], v[184:187], v[116:119]
	v_mfma_f32_16x16x32_bf16 v[104:107], v[216:219], v[192:195], v[104:107]
	v_mfma_f32_16x16x32_bf16 v[100:103], v[224:227], v[192:195], v[100:103]
	v_mfma_f32_16x16x32_bf16 v[88:91], v[216:219], v[200:203], v[88:91]
	v_mfma_f32_16x16x32_bf16 v[84:87], v[224:227], v[200:203], v[84:87]
	v_mfma_f32_16x16x32_bf16 v[72:75], v[216:219], v[208:211], v[72:75]
	v_mfma_f32_16x16x32_bf16 v[68:71], v[224:227], v[208:211], v[68:71]
	s_barrier
	s_setprio 2
	s_mov_b32 m0, s39
	ds_read_b128 v[180:183], v148 offset:16384
	ds_read_b128 v[184:187], v148 offset:17408
	ds_read_b128 v[188:191], v148 offset:18432
	ds_read_b128 v[192:195], v148 offset:19456
	ds_read_b128 v[196:199], v148 offset:20480
	ds_read_b128 v[200:203], v148 offset:21504
	ds_read_b128 v[204:207], v148 offset:22528
	ds_read_b128 v[208:211], v148 offset:23552
	global_load_lds_dwordx4 v132, s[4:5]
	s_mov_b32 m0, s52
	s_nop 0
	global_load_lds_dwordx4 v138, s[4:5]
	s_waitcnt vmcnt(10)
	s_setprio 0
	s_barrier
	s_waitcnt lgkmcnt(0)
	v_mfma_f32_16x16x32_bf16 v[64:67], v[140:143], v[180:183], v[64:67]
	v_mfma_f32_16x16x32_bf16 v[60:63], v[154:157], v[180:183], v[60:63]
	v_mfma_f32_16x16x32_bf16 v[48:51], v[140:143], v[188:191], v[48:51]
	v_mfma_f32_16x16x32_bf16 v[44:47], v[154:157], v[188:191], v[44:47]
	v_mfma_f32_16x16x32_bf16 v[32:35], v[140:143], v[196:199], v[32:35]
	v_mfma_f32_16x16x32_bf16 v[28:31], v[154:157], v[196:199], v[28:31]
	v_mfma_f32_16x16x32_bf16 v[16:19], v[140:143], v[204:207], v[16:19]
	v_mfma_f32_16x16x32_bf16 v[12:15], v[154:157], v[204:207], v[12:15]
	v_mfma_f32_16x16x32_bf16 v[64:67], v[150:153], v[184:187], v[64:67]
	v_mfma_f32_16x16x32_bf16 v[60:63], v[176:179], v[184:187], v[60:63]
	v_mfma_f32_16x16x32_bf16 v[48:51], v[150:153], v[192:195], v[48:51]
	v_mfma_f32_16x16x32_bf16 v[44:47], v[176:179], v[192:195], v[44:47]
	v_mfma_f32_16x16x32_bf16 v[32:35], v[150:153], v[200:203], v[32:35]
	v_mfma_f32_16x16x32_bf16 v[28:31], v[176:179], v[200:203], v[28:31]
	s_barrier
	s_setprio 3
	v_mfma_f32_16x16x32_bf16 v[16:19], v[150:153], v[208:211], v[16:19]
	v_mfma_f32_16x16x32_bf16 v[12:15], v[176:179], v[208:211], v[12:15]
	s_setprio 2
	ds_read_b128 v[140:143], v228 offset:32768
	ds_read_b128 v[150:153], v228 offset:33792
	ds_read_b128 v[154:157], v228 offset:34816
	ds_read_b128 v[176:179], v228 offset:35840
	s_add_u32 s72, s48, 0x4000
	s_addc_u32 s73, s49, 0
	s_add_i32 s74, s74, s29
	s_mov_b32 m0, s74
	s_nop 0
	global_load_lds_dwordx4 v132, s[72:73]
	s_add_i32 m0, s74, 0x2000
	s_nop 0
	global_load_lds_dwordx4 v138, s[72:73]
	s_waitcnt vmcnt(6)
	s_setprio 0
	s_barrier
; #define PG8_STAGE(bufoff, gbase, voff) do { _Pragma("unroll") for (int _i = 0; _i < 2; ++_i) \
;         __builtin_amdgcn_global_load_lds((const unsigned*)((const char*)(gbase) + (voff)[_i]), (LAS unsigned*)(lds + (bufoff) + ldsw + _i * 8192), 16, 0, 0); } while (0)
; #define PG8_LDA(dst, b, h) do { _Pragma("unroll") for (int m = 0; m < 4; ++m) _Pragma("unroll") for (int k = 0; k < 2; ++k) dst[m][k] = *(const LAS bf16x8*)(lds + PG8_SA(b, h) + aoff + m * 2048 + k * 1024); } while (0)
; #define PG8_LDB(dst, b, h) do { _Pragma("unroll") for (int n = 0; n < 2; ++n) _Pragma("unroll") for (int k = 0; k < 2; ++k) dst[n][k] = *(const LAS bf16x8*)(lds + PG8_SB(b, h) + boff + n * 2048 + k * 1024); } while (0)
; #define PG8_MMA(ai, bj, At, Bt) do { __builtin_amdgcn_s_setprio(1); _Pragma("unroll") for (int m = 0; m < 4; ++m) _Pragma("unroll") for (int n = 0; n < 2; ++n) _Pragma("unroll") for (int k = 0; k < 2; ++k) \
;         acc[ai][bj][m][n] = __builtin_amdgcn_mfma_f32_16x16x32_bf16(Bt[n][k], At[m][k], acc[ai][bj][m][n], 0, 0, 0); __builtin_amdgcn_s_setprio(0); } while (0)
; #define PG8_WAIT_V(n) asm volatile("s_waitcnt vmcnt(" #n ")" ::: "memory")
; #define PG8_WAIT_L(n) asm volatile("s_waitcnt lgkmcnt(" #n ")" ::: "memory")
; #define PG8_BAR __builtin_amdgcn_s_barrier()
; #define PG8_SCHED __builtin_amdgcn_sched_barrier(0)
; template <class Epi, class Sched, int LD>
; __device__ __forceinline__ void gemm_phase(LAS unsigned char* lds, const Gemm g, const Sched& S, const Epi& E) {
;     ...
;             PG8_BAR; PG8_WAIT_L(0); PG8_MMA(1, 0, At, B0); PG8_BAR; PG8_SCHED;
;             PG8_STAGE(PG8_SB(0, 1), b2 + hstep, voffB);
;             PG8_WAIT_V(6); PG8_BAR; PG8_MMA(1, 1, At, B1); PG8_BAR;
;             PG8_LDB(B0, 1, 0); PG8_SCHED; PG8_LDA(At, 1, 0); PG8_STAGE(PG8_SA(0, 1), a2 + hstep, voffA);
;             PG8_WAIT_L(8); PG8_BAR; PG8_WAIT_L(0); PG8_MMA(0, 0, At, B0); PG8_BAR; PG8_SCHED;
;             PG8_LDB(B1, 1, 1); PG8_STAGE(PG8_SB(1, 0), b3, voffB);
;             PG8_BAR; PG8_WAIT_L(0); PG8_MMA(0, 1, At, B1); PG8_BAR;
;             PG8_LDA(At, 1, 1); PG8_STAGE(PG8_SA(1, 0), a3, voffA);
;             PG8_BAR; PG8_WAIT_L(0); PG8_MMA(1, 0, At, B0); PG8_BAR; PG8_SCHED;
	v_mfma_f32_16x16x32_bf16 v[56:59], v[212:215], v[180:183], v[56:59]
	v_mfma_f32_16x16x32_bf16 v[52:55], v[220:223], v[180:183], v[52:55]
	v_mfma_f32_16x16x32_bf16 v[40:43], v[212:215], v[188:191], v[40:43]
	v_mfma_f32_16x16x32_bf16 v[36:39], v[220:223], v[188:191], v[36:39]
	v_mfma_f32_16x16x32_bf16 v[24:27], v[212:215], v[196:199], v[24:27]
	v_mfma_f32_16x16x32_bf16 v[20:23], v[220:223], v[196:199], v[20:23]
	v_mfma_f32_16x16x32_bf16 v[8:11], v[212:215], v[204:207], v[8:11]
	v_mfma_f32_16x16x32_bf16 v[4:7], v[220:223], v[204:207], v[4:7]
	v_mfma_f32_16x16x32_bf16 v[56:59], v[216:219], v[184:187], v[56:59]
	v_mfma_f32_16x16x32_bf16 v[52:55], v[224:227], v[184:187], v[52:55]
	v_mfma_f32_16x16x32_bf16 v[40:43], v[216:219], v[192:195], v[40:43]
	v_mfma_f32_16x16x32_bf16 v[36:39], v[224:227], v[192:195], v[36:39]
	v_mfma_f32_16x16x32_bf16 v[24:27], v[216:219], v[200:203], v[24:27]
	v_mfma_f32_16x16x32_bf16 v[20:23], v[224:227], v[200:203], v[20:23]
	v_mfma_f32_16x16x32_bf16 v[8:11], v[216:219], v[208:211], v[8:11]
	v_mfma_f32_16x16x32_bf16 v[4:7], v[224:227], v[208:211], v[4:7]
	s_barrier
	s_setprio 2
	s_add_i32 s72, 0, 0x18000
	s_add_u32 s4, s4, 0x4000
	s_addc_u32 s5, s5, 0
	s_mov_b32 m0, s53
	ds_read_b128 v[180:183], v148 offset:32768
	ds_read_b128 v[184:187], v148 offset:33792
	ds_read_b128 v[188:191], v148 offset:34816
	ds_read_b128 v[192:195], v148 offset:35840
	ds_read_b128 v[196:199], v148 offset:36864
	ds_read_b128 v[200:203], v148 offset:37888
	ds_read_b128 v[204:207], v148 offset:38912
	ds_read_b128 v[208:211], v148 offset:39936
	global_load_lds_dwordx4 v132, s[4:5]
	s_mov_b32 m0, s54
	s_nop 0
	global_load_lds_dwordx4 v138, s[4:5]
	s_waitcnt lgkmcnt(8)
	s_setprio 0
	s_barrier
	s_waitcnt lgkmcnt(0)
	v_mfma_f32_16x16x32_bf16 v[128:131], v[140:143], v[180:183], v[128:131]
	v_mfma_f32_16x16x32_bf16 v[124:127], v[154:157], v[180:183], v[124:127]
	v_mfma_f32_16x16x32_bf16 v[112:115], v[140:143], v[188:191], v[112:115]
	v_mfma_f32_16x16x32_bf16 v[108:111], v[154:157], v[188:191], v[108:111]
	v_mfma_f32_16x16x32_bf16 v[96:99], v[140:143], v[196:199], v[96:99]
	v_mfma_f32_16x16x32_bf16 v[92:95], v[154:157], v[196:199], v[92:95]
	v_mfma_f32_16x16x32_bf16 v[80:83], v[140:143], v[204:207], v[80:83]
	v_mfma_f32_16x16x32_bf16 v[76:79], v[154:157], v[204:207], v[76:79]
	v_mfma_f32_16x16x32_bf16 v[128:131], v[150:153], v[184:187], v[128:131]
	v_mfma_f32_16x16x32_bf16 v[124:127], v[176:179], v[184:187], v[124:127]
	v_mfma_f32_16x16x32_bf16 v[112:115], v[150:153], v[192:195], v[112:115]
	v_mfma_f32_16x16x32_bf16 v[108:111], v[176:179], v[192:195], v[108:111]
	v_mfma_f32_16x16x32_bf16 v[96:99], v[150:153], v[200:203], v[96:99]
	v_mfma_f32_16x16x32_bf16 v[92:95], v[176:179], v[200:203], v[92:95]
	s_barrier
	s_setprio 3
	v_mfma_f32_16x16x32_bf16 v[80:83], v[150:153], v[208:211], v[80:83]
	v_mfma_f32_16x16x32_bf16 v[76:79], v[176:179], v[208:211], v[76:79]
	s_setprio 2
	s_add_i32 s73, 0, 0x1c000
	s_add_u32 s4, s48, 0x8000
	s_addc_u32 s5, s49, 0
	s_add_i32 s72, s72, s29
	ds_read_b128 v[212:215], v228 offset:49152
	ds_read_b128 v[216:219], v228 offset:50176
	ds_read_b128 v[220:223], v228 offset:51200
	ds_read_b128 v[224:227], v228 offset:52224
	s_mov_b32 m0, s72
	s_nop 0
	global_load_lds_dwordx4 v132, s[4:5]
	s_add_i32 m0, s72, 0x2000
	s_nop 0
	global_load_lds_dwordx4 v138, s[4:5]
	s_setprio 0
	s_barrier
	s_waitcnt lgkmcnt(0)
	v_mfma_f32_16x16x32_bf16 v[120:123], v[212:215], v[180:183], v[120:123]
	v_mfma_f32_16x16x32_bf16 v[116:119], v[220:223], v[180:183], v[116:119]
	v_mfma_f32_16x16x32_bf16 v[104:107], v[212:215], v[188:191], v[104:107]
	v_mfma_f32_16x16x32_bf16 v[100:103], v[220:223], v[188:191], v[100:103]
	v_mfma_f32_16x16x32_bf16 v[88:91], v[212:215], v[196:199], v[88:91]
	v_mfma_f32_16x16x32_bf16 v[84:87], v[220:223], v[196:199], v[84:87]
	v_mfma_f32_16x16x32_bf16 v[72:75], v[212:215], v[204:207], v[72:75]
	v_mfma_f32_16x16x32_bf16 v[68:71], v[220:223], v[204:207], v[68:71]
	v_mfma_f32_16x16x32_bf16 v[120:123], v[216:219], v[184:187], v[120:123]
	v_mfma_f32_16x16x32_bf16 v[116:119], v[224:227], v[184:187], v[116:119]
	v_mfma_f32_16x16x32_bf16 v[104:107], v[216:219], v[192:195], v[104:107]
	v_mfma_f32_16x16x32_bf16 v[100:103], v[224:227], v[192:195], v[100:103]
	v_mfma_f32_16x16x32_bf16 v[88:91], v[216:219], v[200:203], v[88:91]
	v_mfma_f32_16x16x32_bf16 v[84:87], v[224:227], v[200:203], v[84:87]
	v_mfma_f32_16x16x32_bf16 v[72:75], v[216:219], v[208:211], v[72:75]
	v_mfma_f32_16x16x32_bf16 v[68:71], v[224:227], v[208:211], v[68:71]
	s_barrier
	s_setprio 2
	s_mov_b32 m0, s55
	ds_read_b128 v[180:183], v148 offset:49152
	ds_read_b128 v[184:187], v148 offset:50176
	ds_read_b128 v[188:191], v148 offset:51200
	ds_read_b128 v[192:195], v148 offset:52224
	ds_read_b128 v[196:199], v148 offset:53248
	ds_read_b128 v[200:203], v148 offset:54272
	ds_read_b128 v[204:207], v148 offset:55296
	ds_read_b128 v[208:211], v148 offset:56320
	global_load_lds_dwordx4 v132, s[50:51]
	s_mov_b32 m0, s56
	s_nop 0
	global_load_lds_dwordx4 v138, s[50:51]
	s_waitcnt vmcnt(10)
	s_setprio 0
	s_barrier
	s_waitcnt lgkmcnt(0)
	v_mfma_f32_16x16x32_bf16 v[64:67], v[140:143], v[180:183], v[64:67]
	v_mfma_f32_16x16x32_bf16 v[60:63], v[154:157], v[180:183], v[60:63]
	v_mfma_f32_16x16x32_bf16 v[48:51], v[140:143], v[188:191], v[48:51]
	v_mfma_f32_16x16x32_bf16 v[44:47], v[154:157], v[188:191], v[44:47]
	v_mfma_f32_16x16x32_bf16 v[32:35], v[140:143], v[196:199], v[32:35]
	v_mfma_f32_16x16x32_bf16 v[28:31], v[154:157], v[196:199], v[28:31]
	v_mfma_f32_16x16x32_bf16 v[16:19], v[140:143], v[204:207], v[16:19]
	v_mfma_f32_16x16x32_bf16 v[12:15], v[154:157], v[204:207], v[12:15]
	v_mfma_f32_16x16x32_bf16 v[64:67], v[150:153], v[184:187], v[64:67]
	v_mfma_f32_16x16x32_bf16 v[60:63], v[176:179], v[184:187], v[60:63]
	v_mfma_f32_16x16x32_bf16 v[48:51], v[150:153], v[192:195], v[48:51]
	v_mfma_f32_16x16x32_bf16 v[44:47], v[176:179], v[192:195], v[44:47]
	v_mfma_f32_16x16x32_bf16 v[32:35], v[150:153], v[200:203], v[32:35]
	v_mfma_f32_16x16x32_bf16 v[28:31], v[176:179], v[200:203], v[28:31]
	s_barrier
; #define PG8_STAGE(bufoff, gbase, voff) do { _Pragma("unroll") for (int _i = 0; _i < 2; ++_i) \
;         __builtin_amdgcn_global_load_lds((const unsigned*)((const char*)(gbase) + (voff)[_i]), (LAS unsigned*)(lds + (bufoff) + ldsw + _i * 8192), 16, 0, 0); } while (0)
; #define PG8_MMA(ai, bj, At, Bt) do { __builtin_amdgcn_s_setprio(1); _Pragma("unroll") for (int m = 0; m < 4; ++m) _Pragma("unroll") for (int n = 0; n < 2; ++n) _Pragma("unroll") for (int k = 0; k < 2; ++k) \
;         acc[ai][bj][m][n] = __builtin_amdgcn_mfma_f32_16x16x32_bf16(Bt[n][k], At[m][k], acc[ai][bj][m][n], 0, 0, 0); __builtin_amdgcn_s_setprio(0); } while (0)
; #define PG8_WAIT_V(n) asm volatile("s_waitcnt vmcnt(" #n ")" ::: "memory")
; #define PG8_BAR __builtin_amdgcn_s_barrier()
;     __device__ __forceinline__ void operator()(const f32x4 (&acc)[2][2][4][2], const Unit& u, int wr, int wc, int fr, int fq) const {
;     ...
;         } else {
;             float* base = PART + (size_t)u.part * (512 * 2048);
; #pragma unroll
;             for (int ai = 0; ai < 2; ++ai)
; #pragma unroll
;                 for (int m = 0; m < 4; ++m) {
;                     float* rowp = base + (size_t)(row0 - 8192 + ai * HALF + m * 16) * D_MODEL + col0;
; #pragma unroll
;                     for (int bj = 0; bj < 2; ++bj)
; #pragma unroll
;                         for (int n = 0; n < 2; ++n) *(f32x4*)(rowp + bj * HALF + n * 16) = acc[ai][bj][m][n];
;                 }
; template <class Epi, class Sched, int LD>
; __device__ __forceinline__ void gemm_phase(LAS unsigned char* lds, const Gemm g, const Sched& S, const Epi& E) {
;     ...
;             PG8_STAGE(PG8_SB(1, 1), b3 + hstep, voffB);
;             PG8_WAIT_V(6); PG8_BAR; PG8_MMA(1, 1, At, B1); PG8_BAR;
;         }
	s_setprio 3
	v_mfma_f32_16x16x32_bf16 v[16:19], v[150:153], v[208:211], v[16:19]
	v_mfma_f32_16x16x32_bf16 v[12:15], v[176:179], v[208:211], v[12:15]
	s_setprio 2
	ds_read_b128 v[140:143], v228
	ds_read_b128 v[150:153], v228 offset:1024
	ds_read_b128 v[154:157], v228 offset:2048
	ds_read_b128 v[176:179], v228 offset:3072
	s_add_u32 s4, s48, 0xc000
	s_addc_u32 s5, s49, 0
	s_add_i32 s48, s73, s29
	s_mov_b32 m0, s48
	s_nop 0
	global_load_lds_dwordx4 v132, s[4:5]
	s_add_i32 m0, s48, 0x2000
	s_nop 0
	global_load_lds_dwordx4 v138, s[4:5]
	s_waitcnt vmcnt(6)
	s_setprio 0
	s_barrier
	v_mfma_f32_16x16x32_bf16 v[56:59], v[212:215], v[180:183], v[56:59]
	v_mfma_f32_16x16x32_bf16 v[52:55], v[220:223], v[180:183], v[52:55]
	v_mfma_f32_16x16x32_bf16 v[40:43], v[212:215], v[188:191], v[40:43]
	v_mfma_f32_16x16x32_bf16 v[36:39], v[220:223], v[188:191], v[36:39]
	v_mfma_f32_16x16x32_bf16 v[24:27], v[212:215], v[196:199], v[24:27]
	v_mfma_f32_16x16x32_bf16 v[20:23], v[220:223], v[196:199], v[20:23]
	v_mfma_f32_16x16x32_bf16 v[8:11], v[212:215], v[204:207], v[8:11]
	v_mfma_f32_16x16x32_bf16 v[4:7], v[220:223], v[204:207], v[4:7]
	v_mfma_f32_16x16x32_bf16 v[56:59], v[216:219], v[184:187], v[56:59]
	v_mfma_f32_16x16x32_bf16 v[52:55], v[224:227], v[184:187], v[52:55]
	v_mfma_f32_16x16x32_bf16 v[40:43], v[216:219], v[192:195], v[40:43]
	v_mfma_f32_16x16x32_bf16 v[36:39], v[224:227], v[192:195], v[36:39]
	v_mfma_f32_16x16x32_bf16 v[24:27], v[216:219], v[200:203], v[24:27]
	v_mfma_f32_16x16x32_bf16 v[20:23], v[224:227], v[200:203], v[20:23]
	v_mfma_f32_16x16x32_bf16 v[8:11], v[216:219], v[208:211], v[8:11]
	v_mfma_f32_16x16x32_bf16 v[4:7], v[224:227], v[208:211], v[4:7]
	s_barrier
	s_setprio 2
	s_add_u32 s46, s46, 0x10000
	s_addc_u32 s47, s47, 0
	s_add_u32 s69, s69, 0x10000
	s_addc_u32 s70, s70, 0
	s_cmp_ge_i32 s71, s65
	s_mov_b32 s4, s71
	s_cbranch_scc0 .LBB0_58
	s_setprio 0
	v_lshl_add_u32 v142, s67, 8, v137
	v_lshl_or_b32 v140, s66, 8, v147
	s_mov_b64 s[4:5], -1
	s_cmp_gt_i32 s18, -1
	v_ashrrev_i32_e32 v141, 31, v140
	v_ashrrev_i32_e32 v143, 31, v142
	s_cbranch_scc0 .LBB0_61
	s_lshl_b64 s[4:5], s[18:19], 22
	v_readlane_b32 s18, v252, 10
	s_add_u32 s4, s18, s4
	v_readlane_b32 s18, v252, 11
	s_addc_u32 s5, s18, s5
	v_lshl_add_u64 v[144:145], v[140:141], 2, s[4:5]
	v_lshlrev_b64 v[150:151], 13, v[142:143]
	s_brev_b32 s4, 63
	v_lshl_add_u64 v[144:145], v[144:145], 0, v[150:151]
	s_mov_b32 s5, -1
	v_lshl_add_u64 v[150:151], v[144:145], 0, s[4:5]
	s_brev_b32 s4, 63
	v_add_co_u32_e32 v152, vcc, s4, v144
	s_mov_b32 s4, 0xfc020000
	s_nop 0
	v_addc_co_u32_e32 v153, vcc, -1, v145, vcc
	s_mov_b32 s5, -1
	global_store_dwordx4 v[152:153], v[128:131], off
	global_store_dwordx4 v[150:151], v[124:127], off offset:64
	global_store_dwordx4 v[150:151], v[120:123], off offset:512
	global_store_dwordx4 v[150:151], v[116:119], off offset:576
	v_lshl_add_u64 v[150:151], v[144:145], 0, s[4:5]
	s_mov_b32 s4, 0xfc020000
	v_add_co_u32_e32 v152, vcc, s4, v144
	s_mov_b32 s4, 0xfc040000
	s_nop 0
	v_addc_co_u32_e32 v153, vcc, -1, v145, vcc
	s_mov_b32 s5, -1
	global_store_dwordx4 v[152:153], v[112:115], off
	global_store_dwordx4 v[150:151], v[108:111], off offset:64
	global_store_dwordx4 v[150:151], v[104:107], off offset:512
	global_store_dwordx4 v[150:151], v[100:103], off offset:576
	v_lshl_add_u64 v[150:151], v[144:145], 0, s[4:5]
	s_mov_b32 s4, 0xfc040000
	v_add_co_u32_e32 v152, vcc, s4, v144
	s_mov_b32 s4, 0xfc060000
	s_nop 0
	v_addc_co_u32_e32 v153, vcc, -1, v145, vcc
	s_mov_b32 s5, -1
	global_store_dwordx4 v[152:153], v[96:99], off
	global_store_dwordx4 v[150:151], v[92:95], off offset:64
	global_store_dwordx4 v[150:151], v[88:91], off offset:512
	global_store_dwordx4 v[150:151], v[84:87], off offset:576
	v_lshl_add_u64 v[150:151], v[144:145], 0, s[4:5]
	s_mov_b32 s4, 0xfc060000
	v_add_co_u32_e32 v152, vcc, s4, v144
	s_mov_b32 s4, 0xfc100000
	s_nop 0
	v_addc_co_u32_e32 v153, vcc, -1, v145, vcc
	s_mov_b32 s5, -1
	global_store_dwordx4 v[152:153], v[80:83], off
	global_store_dwordx4 v[150:151], v[76:79], off offset:64
	global_store_dwordx4 v[150:151], v[72:75], off offset:512
	global_store_dwordx4 v[150:151], v[68:71], off offset:576
	v_lshl_add_u64 v[150:151], v[144:145], 0, s[4:5]
	s_mov_b32 s4, 0xfc100000
	v_add_co_u32_e32 v152, vcc, s4, v144
	s_mov_b32 s4, 0xfc120000
	s_nop 0
	v_addc_co_u32_e32 v153, vcc, -1, v145, vcc
	s_mov_b32 s5, -1
	global_store_dwordx4 v[152:153], v[64:67], off
	global_store_dwordx4 v[150:151], v[60:63], off offset:64
	global_store_dwordx4 v[150:151], v[56:59], off offset:512
	global_store_dwordx4 v[150:151], v[52:55], off offset:576
	v_lshl_add_u64 v[150:151], v[144:145], 0, s[4:5]
	s_mov_b32 s4, 0xfc120000
	v_add_co_u32_e32 v152, vcc, s4, v144
	s_mov_b32 s4, 0xfc140000
	s_nop 0
	v_addc_co_u32_e32 v153, vcc, -1, v145, vcc
	s_mov_b32 s5, -1
	global_store_dwordx4 v[152:153], v[48:51], off
	global_store_dwordx4 v[150:151], v[44:47], off offset:64
	global_store_dwordx4 v[150:151], v[40:43], off offset:512
	global_store_dwordx4 v[150:151], v[36:39], off offset:576
	v_lshl_add_u64 v[150:151], v[144:145], 0, s[4:5]
	s_mov_b32 s4, 0xfc140000
	v_add_co_u32_e32 v152, vcc, s4, v144
	s_mov_b32 s4, 0xfc160000
	s_nop 0
	v_addc_co_u32_e32 v153, vcc, -1, v145, vcc
	s_mov_b32 s5, -1
	global_store_dwordx4 v[152:153], v[32:35], off
	global_store_dwordx4 v[150:151], v[28:31], off offset:64
	global_store_dwordx4 v[150:151], v[24:27], off offset:512
	global_store_dwordx4 v[150:151], v[20:23], off offset:576
	v_lshl_add_u64 v[150:151], v[144:145], 0, s[4:5]
	v_add_co_u32_e32 v144, vcc, 0xfc160000, v144
	s_mov_b64 s[4:5], 0
	s_nop 0
	v_addc_co_u32_e32 v145, vcc, -1, v145, vcc
	global_store_dwordx4 v[144:145], v[16:19], off
	global_store_dwordx4 v[150:151], v[12:15], off offset:64
	global_store_dwordx4 v[150:151], v[8:11], off offset:512
	global_store_dwordx4 v[150:151], v[4:7], off offset:576

; #define PG8_STAGE(bufoff, gbase, voff) do { _Pragma("unroll") for (int _i = 0; _i < 2; ++_i) \
;         __builtin_amdgcn_global_load_lds((const unsigned*)((const char*)(gbase) + (voff)[_i]), (LAS unsigned*)(lds + (bufoff) + ldsw + _i * 8192), 16, 0, 0); } while (0)
; #define PG8_LDA(dst, b, h) do { _Pragma("unroll") for (int m = 0; m < 4; ++m) _Pragma("unroll") for (int k = 0; k < 2; ++k) dst[m][k] = *(const LAS bf16x8*)(lds + PG8_SA(b, h) + aoff + m * 2048 + k * 1024); } while (0)
; #define PG8_LDB(dst, b, h) do { _Pragma("unroll") for (int n = 0; n < 2; ++n) _Pragma("unroll") for (int k = 0; k < 2; ++k) dst[n][k] = *(const LAS bf16x8*)(lds + PG8_SB(b, h) + boff + n * 2048 + k * 1024); } while (0)
; #define PG8_WAIT_V(n) asm volatile("s_waitcnt vmcnt(" #n ")" ::: "memory")
; #define PG8_WAIT_L(n) asm volatile("s_waitcnt lgkmcnt(" #n ")" ::: "memory")
; #define PG8_BAR __builtin_amdgcn_s_barrier()
; #define PG8_SCHED __builtin_amdgcn_sched_barrier(0)
; template <class Epi, class Sched, int LD>
; __device__ __forceinline__ void gemm_phase(LAS unsigned char* lds, const Gemm g, const Sched& S, const Epi& E) {
;     ...
;         for (int t = 0; t < nt; t += 2) {
;             const bool last = (t == nt - 2);
;             const char* a1 = cA + (size_t)(t + 1) * kstep;
;             const char* a2 = last ? nA : cA + (size_t)(t + 2) * kstep; const char* b2 = last ? nB : cB + (size_t)(t + 2) * kstep;
;             const char* a3 = a2 + kstep; const char* b3 = b2 + kstep;
;             PG8_LDB(B0, 0, 0); PG8_SCHED; PG8_LDA(At, 0, 0); PG8_STAGE(PG8_SA(1, 1), a1 + hstep, voffA);
;             PG8_WAIT_L(8); PG8_BAR; PG8_WAIT_L(0); PG8_MMA(0, 0, At, B0); PG8_BAR; PG8_SCHED;
;             PG8_LDB(B1, 0, 1); PG8_STAGE(PG8_SB(0, 0), b2, voffB);
;             PG8_BAR; PG8_WAIT_L(0); PG8_MMA(0, 1, At, B1); PG8_BAR;
;             PG8_LDA(At, 0, 1); PG8_STAGE(PG8_SA(0, 0), a2, voffA);
;             PG8_BAR; PG8_WAIT_L(0); PG8_MMA(1, 0, At, B0); PG8_BAR; PG8_SCHED;
;             PG8_STAGE(PG8_SB(0, 1), b2 + hstep, voffB);
;             PG8_WAIT_V(6); PG8_BAR; PG8_MMA(1, 1, At, B1); PG8_BAR;
;             PG8_LDB(B0, 1, 0); PG8_SCHED; PG8_LDA(At, 1, 0); PG8_STAGE(PG8_SA(0, 1), a2 + hstep, voffA);
;             PG8_WAIT_L(8); PG8_BAR; PG8_WAIT_L(0); PG8_MMA(0, 0, At, B0); PG8_BAR; PG8_SCHED;
.LBB0_501:
	s_add_u32 s4, s54, 0x4000
	s_addc_u32 s5, s55, 0
	s_cmp_eq_u32 s49, 28
	s_cselect_b32 s4, s50, s4
	s_cselect_b32 s5, s51, s5
	s_cselect_b32 s56, s40, s29
	s_cselect_b32 s57, s41, s47
	s_add_u32 s58, s4, 0x8000
	s_addc_u32 s59, s5, 0
	s_add_i32 s69, 0, 0x10000
	s_add_i32 m0, s52, 0xc000
	ds_read_b128 v[180:183], v146
	ds_read_b128 v[184:187], v146 offset:1024
	ds_read_b128 v[188:191], v146 offset:2048
	ds_read_b128 v[192:195], v146 offset:3072
	ds_read_b128 v[196:199], v146 offset:4096
	ds_read_b128 v[200:203], v146 offset:5120
	ds_read_b128 v[204:207], v146 offset:6144
	ds_read_b128 v[208:211], v146 offset:7168
	global_load_lds_dwordx4 v132, s[54:55]
	s_add_i32 m0, s52, 0xe000
	s_nop 0
	global_load_lds_dwordx4 v138, s[54:55]
	s_waitcnt lgkmcnt(8)
	s_setprio 0
	s_barrier
	s_waitcnt lgkmcnt(0)
	v_mfma_f32_16x16x32_bf16 v[128:131], v[148:151], v[180:183], v[128:131]
	v_mfma_f32_16x16x32_bf16 v[124:127], v[156:159], v[180:183], v[124:127]
	v_mfma_f32_16x16x32_bf16 v[120:123], v[148:151], v[188:191], v[120:123]
	v_mfma_f32_16x16x32_bf16 v[116:119], v[156:159], v[188:191], v[116:119]
	v_mfma_f32_16x16x32_bf16 v[104:107], v[148:151], v[196:199], v[104:107]
	v_mfma_f32_16x16x32_bf16 v[100:103], v[156:159], v[196:199], v[100:103]
	v_mfma_f32_16x16x32_bf16 v[88:91], v[148:151], v[204:207], v[88:91]
	v_mfma_f32_16x16x32_bf16 v[84:87], v[156:159], v[204:207], v[84:87]
	v_mfma_f32_16x16x32_bf16 v[128:131], v[152:155], v[184:187], v[128:131]
	v_mfma_f32_16x16x32_bf16 v[124:127], v[176:179], v[184:187], v[124:127]
	v_mfma_f32_16x16x32_bf16 v[120:123], v[152:155], v[192:195], v[120:123]
	v_mfma_f32_16x16x32_bf16 v[116:119], v[176:179], v[192:195], v[116:119]
	v_mfma_f32_16x16x32_bf16 v[104:107], v[152:155], v[200:203], v[104:107]
	v_mfma_f32_16x16x32_bf16 v[100:103], v[176:179], v[200:203], v[100:103]
	s_barrier
	s_setprio 3
	v_mfma_f32_16x16x32_bf16 v[88:91], v[152:155], v[208:211], v[88:91]
	v_mfma_f32_16x16x32_bf16 v[84:87], v[176:179], v[208:211], v[84:87]
	s_setprio 2
	s_add_i32 s72, 0, 0x14000
	s_add_i32 s69, s69, s39
	ds_read_b128 v[212:215], v228 offset:16384
	ds_read_b128 v[216:219], v228 offset:17408
	ds_read_b128 v[220:223], v228 offset:18432
	ds_read_b128 v[224:227], v228 offset:19456
	s_mov_b32 m0, s69
	s_nop 0
	global_load_lds_dwordx4 v132, s[56:57]
	s_add_i32 m0, s69, 0x2000
	s_nop 0
	global_load_lds_dwordx4 v138, s[56:57]
	s_setprio 0
	s_barrier
	s_waitcnt lgkmcnt(0)
	v_mfma_f32_16x16x32_bf16 v[112:115], v[212:215], v[180:183], v[112:115]
	v_mfma_f32_16x16x32_bf16 v[108:111], v[220:223], v[180:183], v[108:111]
	v_mfma_f32_16x16x32_bf16 v[96:99], v[212:215], v[188:191], v[96:99]
	v_mfma_f32_16x16x32_bf16 v[92:95], v[220:223], v[188:191], v[92:95]
	v_mfma_f32_16x16x32_bf16 v[80:83], v[212:215], v[196:199], v[80:83]
	v_mfma_f32_16x16x32_bf16 v[76:79], v[220:223], v[196:199], v[76:79]
	v_mfma_f32_16x16x32_bf16 v[72:75], v[212:215], v[204:207], v[72:75]
	v_mfma_f32_16x16x32_bf16 v[68:71], v[220:223], v[204:207], v[68:71]
	v_mfma_f32_16x16x32_bf16 v[112:115], v[216:219], v[184:187], v[112:115]
	v_mfma_f32_16x16x32_bf16 v[108:111], v[224:227], v[184:187], v[108:111]
	v_mfma_f32_16x16x32_bf16 v[96:99], v[216:219], v[192:195], v[96:99]
	v_mfma_f32_16x16x32_bf16 v[92:95], v[224:227], v[192:195], v[92:95]
	v_mfma_f32_16x16x32_bf16 v[80:83], v[216:219], v[200:203], v[80:83]
	v_mfma_f32_16x16x32_bf16 v[76:79], v[224:227], v[200:203], v[76:79]
	v_mfma_f32_16x16x32_bf16 v[72:75], v[216:219], v[208:211], v[72:75]
	v_mfma_f32_16x16x32_bf16 v[68:71], v[224:227], v[208:211], v[68:71]
	s_barrier
	s_setprio 2
	s_mov_b32 m0, s52
	ds_read_b128 v[180:183], v146 offset:16384
	ds_read_b128 v[184:187], v146 offset:17408
	ds_read_b128 v[188:191], v146 offset:18432
	ds_read_b128 v[192:195], v146 offset:19456
	ds_read_b128 v[196:199], v146 offset:20480
	ds_read_b128 v[200:203], v146 offset:21504
	ds_read_b128 v[204:207], v146 offset:22528
	ds_read_b128 v[208:211], v146 offset:23552
	global_load_lds_dwordx4 v132, s[4:5]
	s_mov_b32 m0, s53
	s_nop 0
	global_load_lds_dwordx4 v138, s[4:5]
	s_waitcnt vmcnt(10)
	s_setprio 0
	s_barrier
	s_waitcnt lgkmcnt(0)
	v_mfma_f32_16x16x32_bf16 v[64:67], v[148:151], v[180:183], v[64:67]
	v_mfma_f32_16x16x32_bf16 v[60:63], v[156:159], v[180:183], v[60:63]
	v_mfma_f32_16x16x32_bf16 v[56:59], v[148:151], v[188:191], v[56:59]
	v_mfma_f32_16x16x32_bf16 v[52:55], v[156:159], v[188:191], v[52:55]
	v_mfma_f32_16x16x32_bf16 v[40:43], v[148:151], v[196:199], v[40:43]
	v_mfma_f32_16x16x32_bf16 v[36:39], v[156:159], v[196:199], v[36:39]
	v_mfma_f32_16x16x32_bf16 v[24:27], v[148:151], v[204:207], v[24:27]
	v_mfma_f32_16x16x32_bf16 v[20:23], v[156:159], v[204:207], v[20:23]
	v_mfma_f32_16x16x32_bf16 v[64:67], v[152:155], v[184:187], v[64:67]
	v_mfma_f32_16x16x32_bf16 v[60:63], v[176:179], v[184:187], v[60:63]
	v_mfma_f32_16x16x32_bf16 v[56:59], v[152:155], v[192:195], v[56:59]
	v_mfma_f32_16x16x32_bf16 v[52:55], v[176:179], v[192:195], v[52:55]
	v_mfma_f32_16x16x32_bf16 v[40:43], v[152:155], v[200:203], v[40:43]
	v_mfma_f32_16x16x32_bf16 v[36:39], v[176:179], v[200:203], v[36:39]
	s_barrier
	s_setprio 3
	v_mfma_f32_16x16x32_bf16 v[24:27], v[152:155], v[208:211], v[24:27]
	v_mfma_f32_16x16x32_bf16 v[20:23], v[176:179], v[208:211], v[20:23]
	s_setprio 2
	ds_read_b128 v[148:151], v228 offset:32768
	ds_read_b128 v[152:155], v228 offset:33792
	ds_read_b128 v[156:159], v228 offset:34816
	ds_read_b128 v[176:179], v228 offset:35840
	s_add_u32 s70, s56, 0x4000
	s_addc_u32 s71, s57, 0
	s_add_i32 s69, s72, s39
	s_mov_b32 m0, s69
	s_nop 0
	global_load_lds_dwordx4 v132, s[70:71]
	s_add_i32 m0, s69, 0x2000
	s_nop 0
	global_load_lds_dwordx4 v138, s[70:71]
	s_waitcnt vmcnt(6)
	s_setprio 0
	s_barrier
; #define PG8_STAGE(bufoff, gbase, voff) do { _Pragma("unroll") for (int _i = 0; _i < 2; ++_i) \
;         __builtin_amdgcn_global_load_lds((const unsigned*)((const char*)(gbase) + (voff)[_i]), (LAS unsigned*)(lds + (bufoff) + ldsw + _i * 8192), 16, 0, 0); } while (0)
; #define PG8_LDA(dst, b, h) do { _Pragma("unroll") for (int m = 0; m < 4; ++m) _Pragma("unroll") for (int k = 0; k < 2; ++k) dst[m][k] = *(const LAS bf16x8*)(lds + PG8_SA(b, h) + aoff + m * 2048 + k * 1024); } while (0)
; #define PG8_LDB(dst, b, h) do { _Pragma("unroll") for (int n = 0; n < 2; ++n) _Pragma("unroll") for (int k = 0; k < 2; ++k) dst[n][k] = *(const LAS bf16x8*)(lds + PG8_SB(b, h) + boff + n * 2048 + k * 1024); } while (0)
; #define PG8_MMA(ai, bj, At, Bt) do { __builtin_amdgcn_s_setprio(1); _Pragma("unroll") for (int m = 0; m < 4; ++m) _Pragma("unroll") for (int n = 0; n < 2; ++n) _Pragma("unroll") for (int k = 0; k < 2; ++k) \
;         acc[ai][bj][m][n] = __builtin_amdgcn_mfma_f32_16x16x32_bf16(Bt[n][k], At[m][k], acc[ai][bj][m][n], 0, 0, 0); __builtin_amdgcn_s_setprio(0); } while (0)
; #define PG8_WAIT_V(n) asm volatile("s_waitcnt vmcnt(" #n ")" ::: "memory")
; #define PG8_WAIT_L(n) asm volatile("s_waitcnt lgkmcnt(" #n ")" ::: "memory")
; #define PG8_BAR __builtin_amdgcn_s_barrier()
; #define PG8_SCHED __builtin_amdgcn_sched_barrier(0)
; template <class Epi, class Sched, int LD>
; __device__ __forceinline__ void gemm_phase(LAS unsigned char* lds, const Gemm g, const Sched& S, const Epi& E) {
;     ...
;             PG8_BAR; PG8_WAIT_L(0); PG8_MMA(1, 0, At, B0); PG8_BAR; PG8_SCHED;
;             PG8_STAGE(PG8_SB(0, 1), b2 + hstep, voffB);
;             PG8_WAIT_V(6); PG8_BAR; PG8_MMA(1, 1, At, B1); PG8_BAR;
;             PG8_LDB(B0, 1, 0); PG8_SCHED; PG8_LDA(At, 1, 0); PG8_STAGE(PG8_SA(0, 1), a2 + hstep, voffA);
;             PG8_WAIT_L(8); PG8_BAR; PG8_WAIT_L(0); PG8_MMA(0, 0, At, B0); PG8_BAR; PG8_SCHED;
;             PG8_LDB(B1, 1, 1); PG8_STAGE(PG8_SB(1, 0), b3, voffB);
;             PG8_BAR; PG8_WAIT_L(0); PG8_MMA(0, 1, At, B1); PG8_BAR;
;             PG8_LDA(At, 1, 1); PG8_STAGE(PG8_SA(1, 0), a3, voffA);
;             PG8_BAR; PG8_WAIT_L(0); PG8_MMA(1, 0, At, B0); PG8_BAR; PG8_SCHED;
	v_mfma_f32_16x16x32_bf16 v[48:51], v[212:215], v[180:183], v[48:51]
	v_mfma_f32_16x16x32_bf16 v[44:47], v[220:223], v[180:183], v[44:47]
	v_mfma_f32_16x16x32_bf16 v[32:35], v[212:215], v[188:191], v[32:35]
	v_mfma_f32_16x16x32_bf16 v[28:31], v[220:223], v[188:191], v[28:31]
	v_mfma_f32_16x16x32_bf16 v[16:19], v[212:215], v[196:199], v[16:19]
	v_mfma_f32_16x16x32_bf16 v[12:15], v[220:223], v[196:199], v[12:15]
	v_mfma_f32_16x16x32_bf16 v[8:11], v[212:215], v[204:207], v[8:11]
	v_mfma_f32_16x16x32_bf16 v[4:7], v[220:223], v[204:207], v[4:7]
	v_mfma_f32_16x16x32_bf16 v[48:51], v[216:219], v[184:187], v[48:51]
	v_mfma_f32_16x16x32_bf16 v[44:47], v[224:227], v[184:187], v[44:47]
	v_mfma_f32_16x16x32_bf16 v[32:35], v[216:219], v[192:195], v[32:35]
	v_mfma_f32_16x16x32_bf16 v[28:31], v[224:227], v[192:195], v[28:31]
	v_mfma_f32_16x16x32_bf16 v[16:19], v[216:219], v[200:203], v[16:19]
	v_mfma_f32_16x16x32_bf16 v[12:15], v[224:227], v[200:203], v[12:15]
	v_mfma_f32_16x16x32_bf16 v[8:11], v[216:219], v[208:211], v[8:11]
	v_mfma_f32_16x16x32_bf16 v[4:7], v[224:227], v[208:211], v[4:7]
	s_barrier
	s_setprio 2
	s_add_i32 s69, 0, 0x18000
	s_add_u32 s4, s4, 0x4000
	s_addc_u32 s5, s5, 0
	s_mov_b32 m0, s60
	ds_read_b128 v[180:183], v146 offset:32768
	ds_read_b128 v[184:187], v146 offset:33792
	ds_read_b128 v[188:191], v146 offset:34816
	ds_read_b128 v[192:195], v146 offset:35840
	ds_read_b128 v[196:199], v146 offset:36864
	ds_read_b128 v[200:203], v146 offset:37888
	ds_read_b128 v[204:207], v146 offset:38912
	ds_read_b128 v[208:211], v146 offset:39936
	global_load_lds_dwordx4 v132, s[4:5]
	s_mov_b32 m0, s61
	s_nop 0
	global_load_lds_dwordx4 v138, s[4:5]
	s_waitcnt lgkmcnt(8)
	s_setprio 0
	s_barrier
	s_waitcnt lgkmcnt(0)
	v_mfma_f32_16x16x32_bf16 v[128:131], v[148:151], v[180:183], v[128:131]
	v_mfma_f32_16x16x32_bf16 v[124:127], v[156:159], v[180:183], v[124:127]
	v_mfma_f32_16x16x32_bf16 v[120:123], v[148:151], v[188:191], v[120:123]
	v_mfma_f32_16x16x32_bf16 v[116:119], v[156:159], v[188:191], v[116:119]
	v_mfma_f32_16x16x32_bf16 v[104:107], v[148:151], v[196:199], v[104:107]
	v_mfma_f32_16x16x32_bf16 v[100:103], v[156:159], v[196:199], v[100:103]
	v_mfma_f32_16x16x32_bf16 v[88:91], v[148:151], v[204:207], v[88:91]
	v_mfma_f32_16x16x32_bf16 v[84:87], v[156:159], v[204:207], v[84:87]
	v_mfma_f32_16x16x32_bf16 v[128:131], v[152:155], v[184:187], v[128:131]
	v_mfma_f32_16x16x32_bf16 v[124:127], v[176:179], v[184:187], v[124:127]
	v_mfma_f32_16x16x32_bf16 v[120:123], v[152:155], v[192:195], v[120:123]
	v_mfma_f32_16x16x32_bf16 v[116:119], v[176:179], v[192:195], v[116:119]
	v_mfma_f32_16x16x32_bf16 v[104:107], v[152:155], v[200:203], v[104:107]
	v_mfma_f32_16x16x32_bf16 v[100:103], v[176:179], v[200:203], v[100:103]
	s_barrier
	s_setprio 3
	v_mfma_f32_16x16x32_bf16 v[88:91], v[152:155], v[208:211], v[88:91]
	v_mfma_f32_16x16x32_bf16 v[84:87], v[176:179], v[208:211], v[84:87]
	s_setprio 2
	s_add_i32 s70, 0, 0x1c000
	s_add_u32 s4, s56, 0x8000
	s_addc_u32 s5, s57, 0
	s_add_i32 s69, s69, s39
	ds_read_b128 v[212:215], v228 offset:49152
	ds_read_b128 v[216:219], v228 offset:50176
	ds_read_b128 v[220:223], v228 offset:51200
	ds_read_b128 v[224:227], v228 offset:52224
	s_mov_b32 m0, s69
	s_nop 0
	global_load_lds_dwordx4 v132, s[4:5]
	s_add_i32 m0, s69, 0x2000
	s_nop 0
	global_load_lds_dwordx4 v138, s[4:5]
	s_setprio 0
	s_barrier
	s_waitcnt lgkmcnt(0)
	v_mfma_f32_16x16x32_bf16 v[112:115], v[212:215], v[180:183], v[112:115]
	v_mfma_f32_16x16x32_bf16 v[108:111], v[220:223], v[180:183], v[108:111]
	v_mfma_f32_16x16x32_bf16 v[96:99], v[212:215], v[188:191], v[96:99]
	v_mfma_f32_16x16x32_bf16 v[92:95], v[220:223], v[188:191], v[92:95]
	v_mfma_f32_16x16x32_bf16 v[80:83], v[212:215], v[196:199], v[80:83]
	v_mfma_f32_16x16x32_bf16 v[76:79], v[220:223], v[196:199], v[76:79]
	v_mfma_f32_16x16x32_bf16 v[72:75], v[212:215], v[204:207], v[72:75]
	v_mfma_f32_16x16x32_bf16 v[68:71], v[220:223], v[204:207], v[68:71]
	v_mfma_f32_16x16x32_bf16 v[112:115], v[216:219], v[184:187], v[112:115]
	v_mfma_f32_16x16x32_bf16 v[108:111], v[224:227], v[184:187], v[108:111]
	v_mfma_f32_16x16x32_bf16 v[96:99], v[216:219], v[192:195], v[96:99]
	v_mfma_f32_16x16x32_bf16 v[92:95], v[224:227], v[192:195], v[92:95]
	v_mfma_f32_16x16x32_bf16 v[80:83], v[216:219], v[200:203], v[80:83]
	v_mfma_f32_16x16x32_bf16 v[76:79], v[224:227], v[200:203], v[76:79]
	v_mfma_f32_16x16x32_bf16 v[72:75], v[216:219], v[208:211], v[72:75]
	v_mfma_f32_16x16x32_bf16 v[68:71], v[224:227], v[208:211], v[68:71]
	s_barrier
	s_setprio 2
	s_mov_b32 m0, s64
	ds_read_b128 v[180:183], v146 offset:49152
	ds_read_b128 v[184:187], v146 offset:50176
	ds_read_b128 v[188:191], v146 offset:51200
	ds_read_b128 v[192:195], v146 offset:52224
	ds_read_b128 v[196:199], v146 offset:53248
	ds_read_b128 v[200:203], v146 offset:54272
	ds_read_b128 v[204:207], v146 offset:55296
	ds_read_b128 v[208:211], v146 offset:56320
	global_load_lds_dwordx4 v132, s[58:59]
	s_mov_b32 m0, s65
	s_nop 0
	global_load_lds_dwordx4 v138, s[58:59]
	s_waitcnt vmcnt(10)
	s_setprio 0
	s_barrier
; #define PG8_STAGE(bufoff, gbase, voff) do { _Pragma("unroll") for (int _i = 0; _i < 2; ++_i) \
;         __builtin_amdgcn_global_load_lds((const unsigned*)((const char*)(gbase) + (voff)[_i]), (LAS unsigned*)(lds + (bufoff) + ldsw + _i * 8192), 16, 0, 0); } while (0)
; #define PG8_LDA(dst, b, h) do { _Pragma("unroll") for (int m = 0; m < 4; ++m) _Pragma("unroll") for (int k = 0; k < 2; ++k) dst[m][k] = *(const LAS bf16x8*)(lds + PG8_SA(b, h) + aoff + m * 2048 + k * 1024); } while (0)
; #define PG8_MMA(ai, bj, At, Bt) do { __builtin_amdgcn_s_setprio(1); _Pragma("unroll") for (int m = 0; m < 4; ++m) _Pragma("unroll") for (int n = 0; n < 2; ++n) _Pragma("unroll") for (int k = 0; k < 2; ++k) \
;         acc[ai][bj][m][n] = __builtin_amdgcn_mfma_f32_16x16x32_bf16(Bt[n][k], At[m][k], acc[ai][bj][m][n], 0, 0, 0); __builtin_amdgcn_s_setprio(0); } while (0)
; #define PG8_WAIT_V(n) asm volatile("s_waitcnt vmcnt(" #n ")" ::: "memory")
; #define PG8_WAIT_L(n) asm volatile("s_waitcnt lgkmcnt(" #n ")" ::: "memory")
; #define PG8_BAR __builtin_amdgcn_s_barrier()
; #define PG8_SCHED __builtin_amdgcn_sched_barrier(0)
;     __device__ __forceinline__ void operator()(const f32x4 (&acc)[2][2][4][2], const Unit& u, int wr, int wc, int fr, int fq) const {
;     ...
;         } else if (wc == 0) {
; #pragma unroll
;             for (int ai = 0; ai < 2; ++ai)
; #pragma unroll
;                 for (int m = 0; m < 4; ++m) {
;                     float* rowp = DT + (size_t)(row0 + ai * HALF + m * 16) * 32 + 8 * fq;
;                     *(f32x4*)rowp = acc[ai][0][m][0]; *(f32x4*)(rowp + 4) = acc[ai][0][m][1];
;                 }
; template <class Epi, class Sched, int LD>
; __device__ __forceinline__ void gemm_phase(LAS unsigned char* lds, const Gemm g, const Sched& S, const Epi& E) {
;     ...
;             PG8_LDA(At, 1, 1); PG8_STAGE(PG8_SA(1, 0), a3, voffA);
;             PG8_BAR; PG8_WAIT_L(0); PG8_MMA(1, 0, At, B0); PG8_BAR; PG8_SCHED;
;             PG8_STAGE(PG8_SB(1, 1), b3 + hstep, voffB);
;             PG8_WAIT_V(6); PG8_BAR; PG8_MMA(1, 1, At, B1); PG8_BAR;
;         }
;         E(acc, cur, wr, wc, fr, fq);
	s_waitcnt lgkmcnt(0)
	v_mfma_f32_16x16x32_bf16 v[64:67], v[148:151], v[180:183], v[64:67]
	v_mfma_f32_16x16x32_bf16 v[60:63], v[156:159], v[180:183], v[60:63]
	v_mfma_f32_16x16x32_bf16 v[56:59], v[148:151], v[188:191], v[56:59]
	v_mfma_f32_16x16x32_bf16 v[52:55], v[156:159], v[188:191], v[52:55]
	v_mfma_f32_16x16x32_bf16 v[40:43], v[148:151], v[196:199], v[40:43]
	v_mfma_f32_16x16x32_bf16 v[36:39], v[156:159], v[196:199], v[36:39]
	v_mfma_f32_16x16x32_bf16 v[24:27], v[148:151], v[204:207], v[24:27]
	v_mfma_f32_16x16x32_bf16 v[20:23], v[156:159], v[204:207], v[20:23]
	v_mfma_f32_16x16x32_bf16 v[64:67], v[152:155], v[184:187], v[64:67]
	v_mfma_f32_16x16x32_bf16 v[60:63], v[176:179], v[184:187], v[60:63]
	v_mfma_f32_16x16x32_bf16 v[56:59], v[152:155], v[192:195], v[56:59]
	v_mfma_f32_16x16x32_bf16 v[52:55], v[176:179], v[192:195], v[52:55]
	v_mfma_f32_16x16x32_bf16 v[40:43], v[152:155], v[200:203], v[40:43]
	v_mfma_f32_16x16x32_bf16 v[36:39], v[176:179], v[200:203], v[36:39]
	s_barrier
	s_setprio 3
	v_mfma_f32_16x16x32_bf16 v[24:27], v[152:155], v[208:211], v[24:27]
	v_mfma_f32_16x16x32_bf16 v[20:23], v[176:179], v[208:211], v[20:23]
	s_setprio 2
	ds_read_b128 v[148:151], v228
	ds_read_b128 v[152:155], v228 offset:1024
	ds_read_b128 v[156:159], v228 offset:2048
	ds_read_b128 v[176:179], v228 offset:3072
	s_add_u32 s4, s56, 0xc000
	s_addc_u32 s5, s57, 0
	s_add_i32 s56, s70, s39
	s_mov_b32 m0, s56
	s_nop 0
	global_load_lds_dwordx4 v132, s[4:5]
	s_add_i32 m0, s56, 0x2000
	s_nop 0
	global_load_lds_dwordx4 v138, s[4:5]
	s_waitcnt vmcnt(6)
	s_setprio 0
	s_barrier
	v_mfma_f32_16x16x32_bf16 v[48:51], v[212:215], v[180:183], v[48:51]
	v_mfma_f32_16x16x32_bf16 v[44:47], v[220:223], v[180:183], v[44:47]
	v_mfma_f32_16x16x32_bf16 v[32:35], v[212:215], v[188:191], v[32:35]
	v_mfma_f32_16x16x32_bf16 v[28:31], v[220:223], v[188:191], v[28:31]
	v_mfma_f32_16x16x32_bf16 v[16:19], v[212:215], v[196:199], v[16:19]
	v_mfma_f32_16x16x32_bf16 v[12:15], v[220:223], v[196:199], v[12:15]
	v_mfma_f32_16x16x32_bf16 v[8:11], v[212:215], v[204:207], v[8:11]
	v_mfma_f32_16x16x32_bf16 v[4:7], v[220:223], v[204:207], v[4:7]
	v_mfma_f32_16x16x32_bf16 v[48:51], v[216:219], v[184:187], v[48:51]
	v_mfma_f32_16x16x32_bf16 v[44:47], v[224:227], v[184:187], v[44:47]
	v_mfma_f32_16x16x32_bf16 v[32:35], v[216:219], v[192:195], v[32:35]
	v_mfma_f32_16x16x32_bf16 v[28:31], v[224:227], v[192:195], v[28:31]
	v_mfma_f32_16x16x32_bf16 v[16:19], v[216:219], v[200:203], v[16:19]
	v_mfma_f32_16x16x32_bf16 v[12:15], v[224:227], v[200:203], v[12:15]
	v_mfma_f32_16x16x32_bf16 v[8:11], v[216:219], v[208:211], v[8:11]
	v_mfma_f32_16x16x32_bf16 v[4:7], v[224:227], v[208:211], v[4:7]
	s_barrier
	s_setprio 2
	s_add_i32 s49, s49, 2
	s_add_u32 s54, s54, 0x10000
	s_addc_u32 s55, s55, 0
	s_add_u32 s29, s29, 0x10000
	s_addc_u32 s47, s47, 0
	s_cmp_gt_u32 s49, 29
	s_cbranch_scc0 .LBB0_501
	s_setprio 0
	v_lshl_add_u32 v142, s68, 8, v137
	s_cmp_gt_i32 s67, 35
	s_mov_b64 s[4:5], -1
	s_cbranch_scc0 .LBB0_506
	s_andn2_b64 vcc, exec, s[42:43]
	s_cbranch_vccnz .LBB0_505
	v_or_b32_e32 v150, 16, v142
	v_ashrrev_i32_e32 v143, 31, v142
	v_ashrrev_i32_e32 v151, 31, v150
	v_lshlrev_b64 v[148:149], 7, v[142:143]
	v_lshlrev_b64 v[150:151], 7, v[150:151]
	v_lshl_add_u64 v[148:149], v[140:141], 0, v[148:149]
	v_lshl_add_u64 v[150:151], v[140:141], 0, v[150:151]
	global_store_dwordx4 v[148:149], v[128:131], off
	global_store_dwordx4 v[148:149], v[124:127], off offset:16
	global_store_dwordx4 v[150:151], v[120:123], off
	global_store_dwordx4 v[150:151], v[116:119], off offset:16
	v_or_b32_e32 v150, 32, v142
	v_ashrrev_i32_e32 v151, 31, v150
	v_lshlrev_b64 v[150:151], 7, v[150:151]
	v_lshl_add_u64 v[150:151], v[140:141], 0, v[150:151]
	global_store_dwordx4 v[150:151], v[104:107], off
	global_store_dwordx4 v[150:151], v[100:103], off offset:16
	v_or_b32_e32 v150, 48, v142
	v_ashrrev_i32_e32 v151, 31, v150
	v_lshlrev_b64 v[150:151], 7, v[150:151]
	v_lshl_add_u64 v[150:151], v[140:141], 0, v[150:151]
	s_mov_b64 s[4:5], 0x4000
	global_store_dwordx4 v[150:151], v[88:91], off
	global_store_dwordx4 v[150:151], v[84:87], off offset:16
	v_lshl_add_u64 v[150:151], v[148:149], 0, s[4:5]
	s_movk_i32 s4, 0x4000
	v_add_co_u32_e32 v152, vcc, s4, v148
	s_mov_b64 s[4:5], 0x4800
	s_nop 0
	v_addc_co_u32_e32 v153, vcc, 0, v149, vcc
	global_store_dwordx4 v[152:153], v[64:67], off
	global_store_dwordx4 v[150:151], v[60:63], off offset:16
	v_lshl_add_u64 v[150:151], v[148:149], 0, s[4:5]
	global_store_dwordx4 v[152:153], v[56:59], off offset:2048
	global_store_dwordx4 v[150:151], v[52:55], off offset:16
	s_mov_b64 s[4:5], 0x5000
	v_add_co_u32_e32 v152, vcc, 0x5000, v148
	v_lshl_add_u64 v[150:151], v[148:149], 0, s[4:5]
	s_nop 0
	v_addc_co_u32_e32 v153, vcc, 0, v149, vcc
	s_mov_b64 s[4:5], 0x5800
	global_store_dwordx4 v[152:153], v[40:43], off
	global_store_dwordx4 v[150:151], v[36:39], off offset:16
	v_lshl_add_u64 v[148:149], v[148:149], 0, s[4:5]
	global_store_dwordx4 v[152:153], v[24:27], off offset:2048
	global_store_dwordx4 v[148:149], v[20:23], off offset:16

; #define PG8_STAGE(bufoff, gbase, voff) do { _Pragma("unroll") for (int _i = 0; _i < 2; ++_i) \
;         __builtin_amdgcn_global_load_lds((const unsigned*)((const char*)(gbase) + (voff)[_i]), (LAS unsigned*)(lds + (bufoff) + ldsw + _i * 8192), 16, 0, 0); } while (0)
; #define PG8_LDA(dst, b, h) do { _Pragma("unroll") for (int m = 0; m < 4; ++m) _Pragma("unroll") for (int k = 0; k < 2; ++k) dst[m][k] = *(const LAS bf16x8*)(lds + PG8_SA(b, h) + aoff + m * 2048 + k * 1024); } while (0)
; #define PG8_LDB(dst, b, h) do { _Pragma("unroll") for (int n = 0; n < 2; ++n) _Pragma("unroll") for (int k = 0; k < 2; ++k) dst[n][k] = *(const LAS bf16x8*)(lds + PG8_SB(b, h) + boff + n * 2048 + k * 1024); } while (0)
; #define PG8_WAIT_V(n) asm volatile("s_waitcnt vmcnt(" #n ")" ::: "memory")
; #define PG8_WAIT_L(n) asm volatile("s_waitcnt lgkmcnt(" #n ")" ::: "memory")
; #define PG8_BAR __builtin_amdgcn_s_barrier()
; #define PG8_SCHED __builtin_amdgcn_sched_barrier(0)
; template <class Epi, class Sched, int LD>
; __device__ __forceinline__ void gemm_phase(LAS unsigned char* lds, const Gemm g, const Sched& S, const Epi& E) {
;     ...
;         for (int t = 0; t < nt; t += 2) {
;             const bool last = (t == nt - 2);
;             const char* a1 = cA + (size_t)(t + 1) * kstep;
;             const char* a2 = last ? nA : cA + (size_t)(t + 2) * kstep; const char* b2 = last ? nB : cB + (size_t)(t + 2) * kstep;
;             const char* a3 = a2 + kstep; const char* b3 = b2 + kstep;
;             PG8_LDB(B0, 0, 0); PG8_SCHED; PG8_LDA(At, 0, 0); PG8_STAGE(PG8_SA(1, 1), a1 + hstep, voffA);
;             PG8_WAIT_L(8); PG8_BAR; PG8_WAIT_L(0); PG8_MMA(0, 0, At, B0); PG8_BAR; PG8_SCHED;
;             PG8_LDB(B1, 0, 1); PG8_STAGE(PG8_SB(0, 0), b2, voffB);
;             PG8_BAR; PG8_WAIT_L(0); PG8_MMA(0, 1, At, B1); PG8_BAR;
;             PG8_LDA(At, 0, 1); PG8_STAGE(PG8_SA(0, 0), a2, voffA);
;             PG8_BAR; PG8_WAIT_L(0); PG8_MMA(1, 0, At, B0); PG8_BAR; PG8_SCHED;
;             PG8_STAGE(PG8_SB(0, 1), b2 + hstep, voffB);
;             PG8_WAIT_V(6); PG8_BAR; PG8_MMA(1, 1, At, B1); PG8_BAR;
;             PG8_LDB(B0, 1, 0); PG8_SCHED; PG8_LDA(At, 1, 0); PG8_STAGE(PG8_SA(0, 1), a2 + hstep, voffA);
;             PG8_WAIT_L(8); PG8_BAR; PG8_WAIT_L(0); PG8_MMA(0, 0, At, B0); PG8_BAR; PG8_SCHED;
.LBB0_899:
	s_add_u32 s4, s50, 0x4000
	s_addc_u32 s5, s51, 0
	s_cmp_eq_u32 s70, 28
	s_cselect_b32 s4, s48, s4
	s_cselect_b32 s5, s49, s5
	s_cselect_b32 s54, s40, s45
	s_cselect_b32 s55, s41, s47
	s_add_u32 s56, s4, 0x8000
	s_addc_u32 s57, s5, 0
	s_add_i32 s71, 0, 0x10000
	s_add_i32 m0, s29, 0xc000
	ds_read_b128 v[180:183], v144
	ds_read_b128 v[184:187], v144 offset:1024
	ds_read_b128 v[188:191], v144 offset:2048
	ds_read_b128 v[192:195], v144 offset:3072
	ds_read_b128 v[196:199], v144 offset:4096
	ds_read_b128 v[200:203], v144 offset:5120
	ds_read_b128 v[204:207], v144 offset:6144
	ds_read_b128 v[208:211], v144 offset:7168
	global_load_lds_dwordx4 v138, s[50:51]
	s_add_i32 m0, s29, 0xe000
	s_nop 0
	global_load_lds_dwordx4 v140, s[50:51]
	s_waitcnt lgkmcnt(8)
	s_setprio 0
	s_barrier
	s_waitcnt lgkmcnt(0)
	v_mfma_f32_16x16x32_bf16 v[128:131], v[146:149], v[180:183], v[128:131]
	v_mfma_f32_16x16x32_bf16 v[120:123], v[154:157], v[180:183], v[120:123]
	v_mfma_f32_16x16x32_bf16 v[112:115], v[146:149], v[188:191], v[112:115]
	v_mfma_f32_16x16x32_bf16 v[104:107], v[154:157], v[188:191], v[104:107]
	v_mfma_f32_16x16x32_bf16 v[96:99], v[146:149], v[196:199], v[96:99]
	v_mfma_f32_16x16x32_bf16 v[88:91], v[154:157], v[196:199], v[88:91]
	v_mfma_f32_16x16x32_bf16 v[80:83], v[146:149], v[204:207], v[80:83]
	v_mfma_f32_16x16x32_bf16 v[72:75], v[154:157], v[204:207], v[72:75]
	v_mfma_f32_16x16x32_bf16 v[128:131], v[150:153], v[184:187], v[128:131]
	v_mfma_f32_16x16x32_bf16 v[120:123], v[176:179], v[184:187], v[120:123]
	v_mfma_f32_16x16x32_bf16 v[112:115], v[150:153], v[192:195], v[112:115]
	v_mfma_f32_16x16x32_bf16 v[104:107], v[176:179], v[192:195], v[104:107]
	v_mfma_f32_16x16x32_bf16 v[96:99], v[150:153], v[200:203], v[96:99]
	v_mfma_f32_16x16x32_bf16 v[88:91], v[176:179], v[200:203], v[88:91]
	s_barrier
	s_setprio 3
	v_mfma_f32_16x16x32_bf16 v[80:83], v[150:153], v[208:211], v[80:83]
	v_mfma_f32_16x16x32_bf16 v[72:75], v[176:179], v[208:211], v[72:75]
	s_setprio 2
	s_add_i32 s74, 0, 0x14000
	s_add_i32 s71, s71, s28
	s_mov_b32 m0, s71
	ds_read_b128 v[212:215], v228 offset:16384
	ds_read_b128 v[216:219], v228 offset:17408
	ds_read_b128 v[220:223], v228 offset:18432
	ds_read_b128 v[224:227], v228 offset:19456
	global_load_lds_dwordx4 v138, s[54:55]
	s_add_i32 m0, s71, 0x2000
	s_nop 0
	global_load_lds_dwordx4 v140, s[54:55]
	s_setprio 0
	s_barrier
	s_waitcnt lgkmcnt(0)
	v_mfma_f32_16x16x32_bf16 v[124:127], v[212:215], v[180:183], v[124:127]
	v_mfma_f32_16x16x32_bf16 v[116:119], v[220:223], v[180:183], v[116:119]
	v_mfma_f32_16x16x32_bf16 v[108:111], v[212:215], v[188:191], v[108:111]
	v_mfma_f32_16x16x32_bf16 v[100:103], v[220:223], v[188:191], v[100:103]
	v_mfma_f32_16x16x32_bf16 v[92:95], v[212:215], v[196:199], v[92:95]
	v_mfma_f32_16x16x32_bf16 v[84:87], v[220:223], v[196:199], v[84:87]
	v_mfma_f32_16x16x32_bf16 v[76:79], v[212:215], v[204:207], v[76:79]
	v_mfma_f32_16x16x32_bf16 v[68:71], v[220:223], v[204:207], v[68:71]
	v_mfma_f32_16x16x32_bf16 v[124:127], v[216:219], v[184:187], v[124:127]
	v_mfma_f32_16x16x32_bf16 v[116:119], v[224:227], v[184:187], v[116:119]
	v_mfma_f32_16x16x32_bf16 v[108:111], v[216:219], v[192:195], v[108:111]
	v_mfma_f32_16x16x32_bf16 v[100:103], v[224:227], v[192:195], v[100:103]
	v_mfma_f32_16x16x32_bf16 v[92:95], v[216:219], v[200:203], v[92:95]
	v_mfma_f32_16x16x32_bf16 v[84:87], v[224:227], v[200:203], v[84:87]
	v_mfma_f32_16x16x32_bf16 v[76:79], v[216:219], v[208:211], v[76:79]
	v_mfma_f32_16x16x32_bf16 v[68:71], v[224:227], v[208:211], v[68:71]
	s_barrier
	s_setprio 2
	s_mov_b32 m0, s29
	ds_read_b128 v[180:183], v144 offset:16384
	ds_read_b128 v[184:187], v144 offset:17408
	ds_read_b128 v[188:191], v144 offset:18432
	ds_read_b128 v[192:195], v144 offset:19456
	ds_read_b128 v[196:199], v144 offset:20480
	ds_read_b128 v[200:203], v144 offset:21504
	ds_read_b128 v[204:207], v144 offset:22528
	ds_read_b128 v[208:211], v144 offset:23552
	global_load_lds_dwordx4 v138, s[4:5]
	s_mov_b32 m0, s39
	s_nop 0
	global_load_lds_dwordx4 v140, s[4:5]
	s_waitcnt vmcnt(10)
	s_setprio 0
	s_barrier
	s_waitcnt lgkmcnt(0)
	v_mfma_f32_16x16x32_bf16 v[64:67], v[146:149], v[180:183], v[64:67]
	v_mfma_f32_16x16x32_bf16 v[56:59], v[154:157], v[180:183], v[56:59]
	v_mfma_f32_16x16x32_bf16 v[48:51], v[146:149], v[188:191], v[48:51]
	v_mfma_f32_16x16x32_bf16 v[40:43], v[154:157], v[188:191], v[40:43]
	v_mfma_f32_16x16x32_bf16 v[32:35], v[146:149], v[196:199], v[32:35]
	v_mfma_f32_16x16x32_bf16 v[24:27], v[154:157], v[196:199], v[24:27]
	v_mfma_f32_16x16x32_bf16 v[16:19], v[146:149], v[204:207], v[16:19]
	v_mfma_f32_16x16x32_bf16 v[8:11], v[154:157], v[204:207], v[8:11]
	v_mfma_f32_16x16x32_bf16 v[64:67], v[150:153], v[184:187], v[64:67]
	v_mfma_f32_16x16x32_bf16 v[56:59], v[176:179], v[184:187], v[56:59]
	v_mfma_f32_16x16x32_bf16 v[48:51], v[150:153], v[192:195], v[48:51]
	v_mfma_f32_16x16x32_bf16 v[40:43], v[176:179], v[192:195], v[40:43]
	v_mfma_f32_16x16x32_bf16 v[32:35], v[150:153], v[200:203], v[32:35]
	v_mfma_f32_16x16x32_bf16 v[24:27], v[176:179], v[200:203], v[24:27]
	s_barrier
	s_setprio 3
	v_mfma_f32_16x16x32_bf16 v[16:19], v[150:153], v[208:211], v[16:19]
	v_mfma_f32_16x16x32_bf16 v[8:11], v[176:179], v[208:211], v[8:11]
	s_setprio 2
	ds_read_b128 v[146:149], v228 offset:32768
	ds_read_b128 v[150:153], v228 offset:33792
	ds_read_b128 v[154:157], v228 offset:34816
	ds_read_b128 v[176:179], v228 offset:35840
	s_add_u32 s72, s54, 0x4000
	s_addc_u32 s73, s55, 0
	s_add_i32 s71, s74, s28
	s_mov_b32 m0, s71
	s_nop 0
	global_load_lds_dwordx4 v138, s[72:73]
	s_add_i32 m0, s71, 0x2000
	s_nop 0
	global_load_lds_dwordx4 v140, s[72:73]
	s_waitcnt vmcnt(6)
	s_setprio 0
	s_barrier
; #define PG8_STAGE(bufoff, gbase, voff) do { _Pragma("unroll") for (int _i = 0; _i < 2; ++_i) \
;         __builtin_amdgcn_global_load_lds((const unsigned*)((const char*)(gbase) + (voff)[_i]), (LAS unsigned*)(lds + (bufoff) + ldsw + _i * 8192), 16, 0, 0); } while (0)
; #define PG8_LDA(dst, b, h) do { _Pragma("unroll") for (int m = 0; m < 4; ++m) _Pragma("unroll") for (int k = 0; k < 2; ++k) dst[m][k] = *(const LAS bf16x8*)(lds + PG8_SA(b, h) + aoff + m * 2048 + k * 1024); } while (0)
; #define PG8_LDB(dst, b, h) do { _Pragma("unroll") for (int n = 0; n < 2; ++n) _Pragma("unroll") for (int k = 0; k < 2; ++k) dst[n][k] = *(const LAS bf16x8*)(lds + PG8_SB(b, h) + boff + n * 2048 + k * 1024); } while (0)
; #define PG8_MMA(ai, bj, At, Bt) do { __builtin_amdgcn_s_setprio(1); _Pragma("unroll") for (int m = 0; m < 4; ++m) _Pragma("unroll") for (int n = 0; n < 2; ++n) _Pragma("unroll") for (int k = 0; k < 2; ++k) \
;         acc[ai][bj][m][n] = __builtin_amdgcn_mfma_f32_16x16x32_bf16(Bt[n][k], At[m][k], acc[ai][bj][m][n], 0, 0, 0); __builtin_amdgcn_s_setprio(0); } while (0)
; #define PG8_WAIT_V(n) asm volatile("s_waitcnt vmcnt(" #n ")" ::: "memory")
; #define PG8_WAIT_L(n) asm volatile("s_waitcnt lgkmcnt(" #n ")" ::: "memory")
; #define PG8_BAR __builtin_amdgcn_s_barrier()
; #define PG8_SCHED __builtin_amdgcn_sched_barrier(0)
; template <class Epi, class Sched, int LD>
; __device__ __forceinline__ void gemm_phase(LAS unsigned char* lds, const Gemm g, const Sched& S, const Epi& E) {
;     ...
;             PG8_BAR; PG8_WAIT_L(0); PG8_MMA(1, 0, At, B0); PG8_BAR; PG8_SCHED;
;             PG8_STAGE(PG8_SB(0, 1), b2 + hstep, voffB);
;             PG8_WAIT_V(6); PG8_BAR; PG8_MMA(1, 1, At, B1); PG8_BAR;
;             PG8_LDB(B0, 1, 0); PG8_SCHED; PG8_LDA(At, 1, 0); PG8_STAGE(PG8_SA(0, 1), a2 + hstep, voffA);
;             PG8_WAIT_L(8); PG8_BAR; PG8_WAIT_L(0); PG8_MMA(0, 0, At, B0); PG8_BAR; PG8_SCHED;
;             PG8_LDB(B1, 1, 1); PG8_STAGE(PG8_SB(1, 0), b3, voffB);
;             PG8_BAR; PG8_WAIT_L(0); PG8_MMA(0, 1, At, B1); PG8_BAR;
;             PG8_LDA(At, 1, 1); PG8_STAGE(PG8_SA(1, 0), a3, voffA);
;             PG8_BAR; PG8_WAIT_L(0); PG8_MMA(1, 0, At, B0); PG8_BAR; PG8_SCHED;
	v_mfma_f32_16x16x32_bf16 v[60:63], v[212:215], v[180:183], v[60:63]
	v_mfma_f32_16x16x32_bf16 v[52:55], v[220:223], v[180:183], v[52:55]
	v_mfma_f32_16x16x32_bf16 v[44:47], v[212:215], v[188:191], v[44:47]
	v_mfma_f32_16x16x32_bf16 v[36:39], v[220:223], v[188:191], v[36:39]
	v_mfma_f32_16x16x32_bf16 v[28:31], v[212:215], v[196:199], v[28:31]
	v_mfma_f32_16x16x32_bf16 v[20:23], v[220:223], v[196:199], v[20:23]
	v_mfma_f32_16x16x32_bf16 v[12:15], v[212:215], v[204:207], v[12:15]
	v_mfma_f32_16x16x32_bf16 v[4:7], v[220:223], v[204:207], v[4:7]
	v_mfma_f32_16x16x32_bf16 v[60:63], v[216:219], v[184:187], v[60:63]
	v_mfma_f32_16x16x32_bf16 v[52:55], v[224:227], v[184:187], v[52:55]
	v_mfma_f32_16x16x32_bf16 v[44:47], v[216:219], v[192:195], v[44:47]
	v_mfma_f32_16x16x32_bf16 v[36:39], v[224:227], v[192:195], v[36:39]
	v_mfma_f32_16x16x32_bf16 v[28:31], v[216:219], v[200:203], v[28:31]
	v_mfma_f32_16x16x32_bf16 v[20:23], v[224:227], v[200:203], v[20:23]
	v_mfma_f32_16x16x32_bf16 v[12:15], v[216:219], v[208:211], v[12:15]
	v_mfma_f32_16x16x32_bf16 v[4:7], v[224:227], v[208:211], v[4:7]
	s_barrier
	s_setprio 2
	s_add_i32 s71, 0, 0x18000
	s_add_u32 s4, s4, 0x4000
	s_addc_u32 s5, s5, 0
	s_mov_b32 m0, s52
	ds_read_b128 v[180:183], v144 offset:32768
	ds_read_b128 v[184:187], v144 offset:33792
	ds_read_b128 v[188:191], v144 offset:34816
	ds_read_b128 v[192:195], v144 offset:35840
	ds_read_b128 v[196:199], v144 offset:36864
	ds_read_b128 v[200:203], v144 offset:37888
	ds_read_b128 v[204:207], v144 offset:38912
	ds_read_b128 v[208:211], v144 offset:39936
	global_load_lds_dwordx4 v138, s[4:5]
	s_mov_b32 m0, s53
	s_nop 0
	global_load_lds_dwordx4 v140, s[4:5]
	s_waitcnt lgkmcnt(8)
	s_setprio 0
	s_barrier
	s_waitcnt lgkmcnt(0)
	v_mfma_f32_16x16x32_bf16 v[128:131], v[146:149], v[180:183], v[128:131]
	v_mfma_f32_16x16x32_bf16 v[120:123], v[154:157], v[180:183], v[120:123]
	v_mfma_f32_16x16x32_bf16 v[112:115], v[146:149], v[188:191], v[112:115]
	v_mfma_f32_16x16x32_bf16 v[104:107], v[154:157], v[188:191], v[104:107]
	v_mfma_f32_16x16x32_bf16 v[96:99], v[146:149], v[196:199], v[96:99]
	v_mfma_f32_16x16x32_bf16 v[88:91], v[154:157], v[196:199], v[88:91]
	v_mfma_f32_16x16x32_bf16 v[80:83], v[146:149], v[204:207], v[80:83]
	v_mfma_f32_16x16x32_bf16 v[72:75], v[154:157], v[204:207], v[72:75]
	v_mfma_f32_16x16x32_bf16 v[128:131], v[150:153], v[184:187], v[128:131]
	v_mfma_f32_16x16x32_bf16 v[120:123], v[176:179], v[184:187], v[120:123]
	v_mfma_f32_16x16x32_bf16 v[112:115], v[150:153], v[192:195], v[112:115]
	v_mfma_f32_16x16x32_bf16 v[104:107], v[176:179], v[192:195], v[104:107]
	v_mfma_f32_16x16x32_bf16 v[96:99], v[150:153], v[200:203], v[96:99]
	v_mfma_f32_16x16x32_bf16 v[88:91], v[176:179], v[200:203], v[88:91]
	s_barrier
	s_setprio 3
	v_mfma_f32_16x16x32_bf16 v[80:83], v[150:153], v[208:211], v[80:83]
	v_mfma_f32_16x16x32_bf16 v[72:75], v[176:179], v[208:211], v[72:75]
	s_setprio 2
	s_add_i32 s72, 0, 0x1c000
	s_add_u32 s4, s54, 0x8000
	s_addc_u32 s5, s55, 0
	s_add_i32 s71, s71, s28
	s_mov_b32 m0, s71
	ds_read_b128 v[212:215], v228 offset:49152
	ds_read_b128 v[216:219], v228 offset:50176
	ds_read_b128 v[220:223], v228 offset:51200
	ds_read_b128 v[224:227], v228 offset:52224
	global_load_lds_dwordx4 v138, s[4:5]
	s_add_i32 m0, s71, 0x2000
	s_nop 0
	global_load_lds_dwordx4 v140, s[4:5]
	s_setprio 0
	s_barrier
	s_waitcnt lgkmcnt(0)
	v_mfma_f32_16x16x32_bf16 v[124:127], v[212:215], v[180:183], v[124:127]
	v_mfma_f32_16x16x32_bf16 v[116:119], v[220:223], v[180:183], v[116:119]
	v_mfma_f32_16x16x32_bf16 v[108:111], v[212:215], v[188:191], v[108:111]
	v_mfma_f32_16x16x32_bf16 v[100:103], v[220:223], v[188:191], v[100:103]
	v_mfma_f32_16x16x32_bf16 v[92:95], v[212:215], v[196:199], v[92:95]
	v_mfma_f32_16x16x32_bf16 v[84:87], v[220:223], v[196:199], v[84:87]
	v_mfma_f32_16x16x32_bf16 v[76:79], v[212:215], v[204:207], v[76:79]
	v_mfma_f32_16x16x32_bf16 v[68:71], v[220:223], v[204:207], v[68:71]
	v_mfma_f32_16x16x32_bf16 v[124:127], v[216:219], v[184:187], v[124:127]
	v_mfma_f32_16x16x32_bf16 v[116:119], v[224:227], v[184:187], v[116:119]
	v_mfma_f32_16x16x32_bf16 v[108:111], v[216:219], v[192:195], v[108:111]
	v_mfma_f32_16x16x32_bf16 v[100:103], v[224:227], v[192:195], v[100:103]
	v_mfma_f32_16x16x32_bf16 v[92:95], v[216:219], v[200:203], v[92:95]
	v_mfma_f32_16x16x32_bf16 v[84:87], v[224:227], v[200:203], v[84:87]
	v_mfma_f32_16x16x32_bf16 v[76:79], v[216:219], v[208:211], v[76:79]
	v_mfma_f32_16x16x32_bf16 v[68:71], v[224:227], v[208:211], v[68:71]
	s_barrier
	s_setprio 2
	s_mov_b32 m0, s60
	ds_read_b128 v[180:183], v144 offset:49152
	ds_read_b128 v[184:187], v144 offset:50176
	ds_read_b128 v[188:191], v144 offset:51200
	ds_read_b128 v[192:195], v144 offset:52224
	ds_read_b128 v[196:199], v144 offset:53248
	ds_read_b128 v[200:203], v144 offset:54272
	ds_read_b128 v[204:207], v144 offset:55296
	ds_read_b128 v[208:211], v144 offset:56320
	global_load_lds_dwordx4 v138, s[56:57]
	s_mov_b32 m0, s61
	s_nop 0
	global_load_lds_dwordx4 v140, s[56:57]
	s_waitcnt vmcnt(10)
	s_setprio 0
	s_barrier
	s_waitcnt lgkmcnt(0)
	v_mfma_f32_16x16x32_bf16 v[64:67], v[146:149], v[180:183], v[64:67]
	v_mfma_f32_16x16x32_bf16 v[56:59], v[154:157], v[180:183], v[56:59]
	v_mfma_f32_16x16x32_bf16 v[48:51], v[146:149], v[188:191], v[48:51]
	v_mfma_f32_16x16x32_bf16 v[40:43], v[154:157], v[188:191], v[40:43]
	v_mfma_f32_16x16x32_bf16 v[32:35], v[146:149], v[196:199], v[32:35]
	v_mfma_f32_16x16x32_bf16 v[24:27], v[154:157], v[196:199], v[24:27]
	v_mfma_f32_16x16x32_bf16 v[16:19], v[146:149], v[204:207], v[16:19]
	v_mfma_f32_16x16x32_bf16 v[8:11], v[154:157], v[204:207], v[8:11]
	v_mfma_f32_16x16x32_bf16 v[64:67], v[150:153], v[184:187], v[64:67]
	v_mfma_f32_16x16x32_bf16 v[56:59], v[176:179], v[184:187], v[56:59]
	v_mfma_f32_16x16x32_bf16 v[48:51], v[150:153], v[192:195], v[48:51]
	v_mfma_f32_16x16x32_bf16 v[40:43], v[176:179], v[192:195], v[40:43]
	v_mfma_f32_16x16x32_bf16 v[32:35], v[150:153], v[200:203], v[32:35]
	v_mfma_f32_16x16x32_bf16 v[24:27], v[176:179], v[200:203], v[24:27]
	s_barrier
; __device__ __forceinline__ unsigned cvt_pk_bf16(float lo, float hi) { f32x2 v = {lo, hi}; bf16x2v b = __builtin_convertvector(v, bf16x2v); return __builtin_bit_cast(unsigned, b); }
; __device__ __forceinline__ float silu_f(float x) { return x * __builtin_amdgcn_rcpf(1.f + __expf(-x)); }
; #define PG8_STAGE(bufoff, gbase, voff) do { _Pragma("unroll") for (int _i = 0; _i < 2; ++_i) \
;         __builtin_amdgcn_global_load_lds((const unsigned*)((const char*)(gbase) + (voff)[_i]), (LAS unsigned*)(lds + (bufoff) + ldsw + _i * 8192), 16, 0, 0); } while (0)
; #define PG8_LDA(dst, b, h) do { _Pragma("unroll") for (int m = 0; m < 4; ++m) _Pragma("unroll") for (int k = 0; k < 2; ++k) dst[m][k] = *(const LAS bf16x8*)(lds + PG8_SA(b, h) + aoff + m * 2048 + k * 1024); } while (0)
; #define PG8_WAIT_V(n) asm volatile("s_waitcnt vmcnt(" #n ")" ::: "memory")
; #define PG8_WAIT_L(n) asm volatile("s_waitcnt lgkmcnt(" #n ")" ::: "memory")
; #define PG8_BAR __builtin_amdgcn_s_barrier()
;     __device__ __forceinline__ void operator()(const f32x4 (&acc)[2][2][4][2], const Unit& u, int wr, int wc, int fr, int fq) const {
;         const int row0 = u.pm * BM + wr * 64 + fr, col0 = u.pn * 128 + wc * 32 + 8 * fq;
; #pragma unroll
;         for (int ai = 0; ai < 2; ++ai)
; #pragma unroll
;             for (int m = 0; m < 4; ++m) {
;                 bf16_t* rowp = O + img_off(row0 + ai * HALF + m * 16, col0, D_FF / 64);
;                 const f32x4 g0 = acc[ai][0][m][0], g1 = acc[ai][0][m][1], u0 = acc[ai][1][m][0], u1 = acc[ai][1][m][1];
;                 u32x4 w;
;                 w.x = cvt_pk_bf16(silu_f(g0[0]) * u0[0], silu_f(g0[1]) * u0[1]); w.y = cvt_pk_bf16(silu_f(g0[2]) * u0[2], silu_f(g0[3]) * u0[3]);
;                 w.z = cvt_pk_bf16(silu_f(g1[0]) * u1[0], silu_f(g1[1]) * u1[1]); w.w = cvt_pk_bf16(silu_f(g1[2]) * u1[2], silu_f(g1[3]) * u1[3]);
;                 *(u32x4*)rowp = w;
; template <class Epi, class Sched, int LD>
; __device__ __forceinline__ void gemm_phase(LAS unsigned char* lds, const Gemm g, const Sched& S, const Epi& E) {
;     ...
;             PG8_LDA(At, 1, 1); PG8_STAGE(PG8_SA(1, 0), a3, voffA);
;             PG8_BAR; PG8_WAIT_L(0); PG8_MMA(1, 0, At, B0); PG8_BAR; PG8_SCHED;
;             PG8_STAGE(PG8_SB(1, 1), b3 + hstep, voffB);
;             PG8_WAIT_V(6); PG8_BAR; PG8_MMA(1, 1, At, B1); PG8_BAR;
;         }
	s_setprio 3
	v_mfma_f32_16x16x32_bf16 v[16:19], v[150:153], v[208:211], v[16:19]
	v_mfma_f32_16x16x32_bf16 v[8:11], v[176:179], v[208:211], v[8:11]
	s_setprio 2
	ds_read_b128 v[146:149], v228
	ds_read_b128 v[150:153], v228 offset:1024
	ds_read_b128 v[154:157], v228 offset:2048
	ds_read_b128 v[176:179], v228 offset:3072
	s_add_u32 s4, s54, 0xc000
	s_addc_u32 s5, s55, 0
	s_add_i32 s54, s72, s28
	s_mov_b32 m0, s54
	s_nop 0
	global_load_lds_dwordx4 v138, s[4:5]
	s_add_i32 m0, s54, 0x2000
	s_nop 0
	global_load_lds_dwordx4 v140, s[4:5]
	s_waitcnt vmcnt(6)
	s_setprio 0
	s_barrier
	v_mfma_f32_16x16x32_bf16 v[60:63], v[212:215], v[180:183], v[60:63]
	v_mfma_f32_16x16x32_bf16 v[52:55], v[220:223], v[180:183], v[52:55]
	v_mfma_f32_16x16x32_bf16 v[44:47], v[212:215], v[188:191], v[44:47]
	v_mfma_f32_16x16x32_bf16 v[36:39], v[220:223], v[188:191], v[36:39]
	v_mfma_f32_16x16x32_bf16 v[28:31], v[212:215], v[196:199], v[28:31]
	v_mfma_f32_16x16x32_bf16 v[20:23], v[220:223], v[196:199], v[20:23]
	v_mfma_f32_16x16x32_bf16 v[12:15], v[212:215], v[204:207], v[12:15]
	v_mfma_f32_16x16x32_bf16 v[4:7], v[220:223], v[204:207], v[4:7]
	v_mfma_f32_16x16x32_bf16 v[60:63], v[216:219], v[184:187], v[60:63]
	v_mfma_f32_16x16x32_bf16 v[52:55], v[224:227], v[184:187], v[52:55]
	v_mfma_f32_16x16x32_bf16 v[44:47], v[216:219], v[192:195], v[44:47]
	v_mfma_f32_16x16x32_bf16 v[36:39], v[224:227], v[192:195], v[36:39]
	v_mfma_f32_16x16x32_bf16 v[28:31], v[216:219], v[200:203], v[28:31]
	v_mfma_f32_16x16x32_bf16 v[20:23], v[224:227], v[200:203], v[20:23]
	v_mfma_f32_16x16x32_bf16 v[12:15], v[216:219], v[208:211], v[12:15]
	v_mfma_f32_16x16x32_bf16 v[4:7], v[224:227], v[208:211], v[4:7]
	s_barrier
	s_setprio 2
	s_add_i32 s70, s70, 2
	s_add_u32 s50, s50, 0x10000
	s_addc_u32 s51, s51, 0
	s_add_u32 s45, s45, 0x10000
	s_addc_u32 s47, s47, 0
	s_cmp_gt_u32 s70, 29
	s_cbranch_scc0 .LBB0_899
	s_setprio 0
	v_mul_f32_e32 v148, 0xbfb8aa3b, v128
	v_mul_f32_e32 v149, 0xbfb8aa3b, v129
	v_exp_f32_e32 v148, v148
	v_exp_f32_e32 v149, v149
	s_lshl_b32 s5, s69, 8
	s_add_i32 s5, s5, s58
	v_add_f32_e32 v148, 1.0, v148
	v_add_f32_e32 v149, 1.0, v149
	v_rcp_f32_e32 v148, v148
	v_rcp_f32_e32 v149, v149
	s_lshl_b32 s4, s68, 7
	s_or_b32 s4, s4, s59
	s_ashr_i32 s45, s5, 8
	v_pk_mul_f32 v[128:129], v[128:129], v[148:149]
	s_ashr_i32 s4, s4, 6
	v_pk_mul_f32 v[124:125], v[128:129], v[124:125]
	s_mulk_i32 s45, 0x58
	v_cvt_pk_bf16_f32 v124, v124, v125
	v_mul_f32_e32 v125, 0xbfb8aa3b, v130
	v_exp_f32_e32 v125, v125
	s_add_i32 s50, s45, s4
	s_ashr_i32 s51, s50, 31
	s_lshl_b64 s[50:51], s[50:51], 15
	v_add_f32_e32 v125, 1.0, v125
	v_rcp_f32_e32 v128, v125
	v_mul_f32_e32 v125, 0xbfb8aa3b, v131
	v_exp_f32_e32 v125, v125
	s_add_u32 s45, s16, s50
	s_addc_u32 s47, s17, s51
	s_lshl_b32 s50, s5, 7
	v_add_f32_e32 v125, 1.0, v125
	v_rcp_f32_e32 v129, v125
	s_and_b32 s50, s50, 0x4000
	s_add_u32 s50, s45, s50
	s_addc_u32 s51, s47, 0
	v_pk_mul_f32 v[128:129], v[130:131], v[128:129]
	s_or_b32 s45, s5, 16
	v_pk_mul_f32 v[126:127], v[128:129], v[126:127]
	s_lshr_b32 s45, s45, 3
	v_cvt_pk_bf16_f32 v125, v126, v127
	v_mul_f32_e32 v126, 0xbfb8aa3b, v120
	v_mul_f32_e32 v127, 0xbfb8aa3b, v121
	v_exp_f32_e32 v126, v126
	v_exp_f32_e32 v127, v127
	v_or_b32_e32 v145, s5, v137
	s_and_b32 s45, s45, 10
	v_add_f32_e32 v126, 1.0, v126
	v_add_f32_e32 v127, 1.0, v127
	v_rcp_f32_e32 v126, v126
	v_rcp_f32_e32 v127, v127
	v_lshlrev_b32_e32 v132, 6, v145
	v_lshlrev_b32_e32 v146, 2, v145
	s_or_b32 s45, s45, s64
	v_pk_mul_f32 v[120:121], v[120:121], v[126:127]
	v_and_or_b32 v132, v132, s15, v142
	v_pk_mul_f32 v[116:117], v[120:121], v[116:117]
	v_and_b32_e32 v146, 32, v146
	v_cvt_pk_bf16_f32 v126, v116, v117
	v_mul_f32_e32 v116, 0xbfb8aa3b, v122
	v_mul_f32_e32 v117, 0xbfb8aa3b, v123
	v_exp_f32_e32 v116, v116
	v_exp_f32_e32 v117, v117
	s_lshl_b32 s45, s45, 10
	v_bitop3_b32 v147, v132, s65, v146 bitop3:0xde
	v_add_f32_e32 v116, 1.0, v116
	v_add_f32_e32 v117, 1.0, v117
	v_rcp_f32_e32 v116, v116
	v_rcp_f32_e32 v117, v117
	s_and_b64 vcc, exec, s[42:43]
	s_mov_b32 s68, s44
	s_mov_b32 s69, s46
	v_pk_mul_f32 v[116:117], v[122:123], v[116:117]
	s_mov_b64 s[54:55], s[40:41]
	v_pk_mul_f32 v[116:117], v[116:117], v[118:119]
	v_bitop3_b32 v118, v132, s45, v146 bitop3:0xde
	v_cvt_pk_bf16_f32 v127, v116, v117
	v_mul_f32_e32 v116, 0xbfb8aa3b, v112
	v_mul_f32_e32 v117, 0xbfb8aa3b, v113
	v_exp_f32_e32 v116, v116
	v_exp_f32_e32 v117, v117
	s_or_b32 s45, s5, 32
	s_or_b32 s5, s5, 48
	v_add_f32_e32 v116, 1.0, v116
	v_add_f32_e32 v117, 1.0, v117
	v_rcp_f32_e32 v116, v116
	v_rcp_f32_e32 v117, v117
	s_lshr_b32 s45, s45, 3
	s_lshr_b32 s5, s5, 3
	s_and_b32 s45, s45, 12
	v_pk_mul_f32 v[112:113], v[112:113], v[116:117]
	s_and_b32 s5, s5, 14
	v_pk_mul_f32 v[108:109], v[112:113], v[108:109]
	s_or_b32 s45, s45, s64
	v_cvt_pk_bf16_f32 v108, v108, v109
	v_mul_f32_e32 v109, 0xbfb8aa3b, v114
	v_exp_f32_e32 v109, v109
	s_or_b32 s5, s5, s64
	s_lshl_b32 s45, s45, 10
	s_lshl_b32 s5, s5, 10
	v_add_f32_e32 v109, 1.0, v109
	v_rcp_f32_e32 v112, v109
	v_mul_f32_e32 v109, 0xbfb8aa3b, v115
	v_exp_f32_e32 v109, v109
	global_store_dwordx4 v147, v[124:127], s[50:51]
	v_add_f32_e32 v109, 1.0, v109
	v_rcp_f32_e32 v113, v109
	s_nop 0
	v_pk_mul_f32 v[112:113], v[114:115], v[112:113]
	s_nop 0
	v_pk_mul_f32 v[110:111], v[112:113], v[110:111]
	s_nop 0
	v_cvt_pk_bf16_f32 v109, v110, v111
	v_mul_f32_e32 v110, 0xbfb8aa3b, v104
	v_mul_f32_e32 v111, 0xbfb8aa3b, v105
	v_exp_f32_e32 v110, v110
	v_exp_f32_e32 v111, v111
	v_add_f32_e32 v110, 1.0, v110
	v_add_f32_e32 v111, 1.0, v111
	v_rcp_f32_e32 v110, v110
	v_rcp_f32_e32 v111, v111
	s_nop 0
	v_pk_mul_f32 v[104:105], v[104:105], v[110:111]
	s_nop 0
; __device__ __forceinline__ unsigned cvt_pk_bf16(float lo, float hi) { f32x2 v = {lo, hi}; bf16x2v b = __builtin_convertvector(v, bf16x2v); return __builtin_bit_cast(unsigned, b); }
; __device__ __forceinline__ float silu_f(float x) { return x * __builtin_amdgcn_rcpf(1.f + __expf(-x)); }
;     __device__ __forceinline__ void operator()(const f32x4 (&acc)[2][2][4][2], const Unit& u, int wr, int wc, int fr, int fq) const {
;         const int row0 = u.pm * BM + wr * 64 + fr, col0 = u.pn * 128 + wc * 32 + 8 * fq;
; #pragma unroll
;         for (int ai = 0; ai < 2; ++ai)
; #pragma unroll
;             for (int m = 0; m < 4; ++m) {
;                 bf16_t* rowp = O + img_off(row0 + ai * HALF + m * 16, col0, D_FF / 64);
;                 const f32x4 g0 = acc[ai][0][m][0], g1 = acc[ai][0][m][1], u0 = acc[ai][1][m][0], u1 = acc[ai][1][m][1];
;                 u32x4 w;
;                 w.x = cvt_pk_bf16(silu_f(g0[0]) * u0[0], silu_f(g0[1]) * u0[1]); w.y = cvt_pk_bf16(silu_f(g0[2]) * u0[2], silu_f(g0[3]) * u0[3]);
;                 w.z = cvt_pk_bf16(silu_f(g1[0]) * u1[0], silu_f(g1[1]) * u1[1]); w.w = cvt_pk_bf16(silu_f(g1[2]) * u1[2], silu_f(g1[3]) * u1[3]);
;                 *(u32x4*)rowp = w;
	v_pk_mul_f32 v[100:101], v[104:105], v[100:101]
	s_nop 0
	v_cvt_pk_bf16_f32 v110, v100, v101
	v_mul_f32_e32 v100, 0xbfb8aa3b, v106
	v_mul_f32_e32 v101, 0xbfb8aa3b, v107
	v_exp_f32_e32 v100, v100
	v_exp_f32_e32 v101, v101
	v_add_f32_e32 v100, 1.0, v100
	v_add_f32_e32 v101, 1.0, v101
	v_rcp_f32_e32 v100, v100
	v_rcp_f32_e32 v101, v101
	s_nop 0
	v_pk_mul_f32 v[100:101], v[106:107], v[100:101]
	s_nop 0
	v_pk_mul_f32 v[100:101], v[100:101], v[102:103]
	v_bitop3_b32 v102, v132, s45, v146 bitop3:0xde
	v_cvt_pk_bf16_f32 v111, v100, v101
	v_mul_f32_e32 v100, 0xbfb8aa3b, v96
	v_mul_f32_e32 v101, 0xbfb8aa3b, v97
	v_exp_f32_e32 v100, v100
	v_exp_f32_e32 v101, v101
	global_store_dwordx4 v118, v[108:111], s[50:51]
	v_add_f32_e32 v100, 1.0, v100
	v_add_f32_e32 v101, 1.0, v101
	v_rcp_f32_e32 v100, v100
	v_rcp_f32_e32 v101, v101
	s_nop 0
	v_pk_mul_f32 v[96:97], v[96:97], v[100:101]
	s_nop 0
	v_pk_mul_f32 v[92:93], v[96:97], v[92:93]
	s_nop 0
	v_cvt_pk_bf16_f32 v92, v92, v93
	v_mul_f32_e32 v93, 0xbfb8aa3b, v98
	v_exp_f32_e32 v93, v93
	s_nop 0
	v_add_f32_e32 v93, 1.0, v93
	v_rcp_f32_e32 v96, v93
	v_mul_f32_e32 v93, 0xbfb8aa3b, v99
	v_exp_f32_e32 v93, v93
	s_nop 0
	v_add_f32_e32 v93, 1.0, v93
	v_rcp_f32_e32 v97, v93
	s_nop 0
	v_pk_mul_f32 v[96:97], v[98:99], v[96:97]
	s_nop 0
	v_pk_mul_f32 v[94:95], v[96:97], v[94:95]
	s_nop 0
	v_cvt_pk_bf16_f32 v93, v94, v95
	v_mul_f32_e32 v94, 0xbfb8aa3b, v88
	v_mul_f32_e32 v95, 0xbfb8aa3b, v89
	v_exp_f32_e32 v94, v94
	v_exp_f32_e32 v95, v95
	v_add_f32_e32 v94, 1.0, v94
	v_add_f32_e32 v95, 1.0, v95
	v_rcp_f32_e32 v94, v94
	v_rcp_f32_e32 v95, v95
	s_nop 0
	v_pk_mul_f32 v[88:89], v[88:89], v[94:95]
	s_nop 0
	v_pk_mul_f32 v[84:85], v[88:89], v[84:85]
	s_nop 0
	v_cvt_pk_bf16_f32 v94, v84, v85
	v_mul_f32_e32 v84, 0xbfb8aa3b, v90
	v_mul_f32_e32 v85, 0xbfb8aa3b, v91
	v_exp_f32_e32 v84, v84
	v_exp_f32_e32 v85, v85
	v_add_f32_e32 v84, 1.0, v84
	v_add_f32_e32 v85, 1.0, v85
	v_rcp_f32_e32 v84, v84
	v_rcp_f32_e32 v85, v85
	s_nop 0
	v_pk_mul_f32 v[84:85], v[90:91], v[84:85]
	s_nop 0
	v_pk_mul_f32 v[84:85], v[84:85], v[86:87]
	v_bitop3_b32 v86, v132, s5, v146 bitop3:0xde
	v_cvt_pk_bf16_f32 v95, v84, v85
	v_mul_f32_e32 v84, 0xbfb8aa3b, v80
	v_mul_f32_e32 v85, 0xbfb8aa3b, v81
	v_exp_f32_e32 v84, v84
	v_exp_f32_e32 v85, v85
	global_store_dwordx4 v102, v[92:95], s[50:51]
	v_add_f32_e32 v84, 1.0, v84
	v_add_f32_e32 v85, 1.0, v85
	v_rcp_f32_e32 v84, v84
	v_rcp_f32_e32 v85, v85
	s_nop 0
	v_pk_mul_f32 v[80:81], v[80:81], v[84:85]
	s_nop 0
	v_pk_mul_f32 v[76:77], v[80:81], v[76:77]
	s_nop 0
	v_cvt_pk_bf16_f32 v76, v76, v77
	v_mul_f32_e32 v77, 0xbfb8aa3b, v82
	v_exp_f32_e32 v77, v77
	s_nop 0
	v_add_f32_e32 v77, 1.0, v77
	v_rcp_f32_e32 v80, v77
	v_mul_f32_e32 v77, 0xbfb8aa3b, v83
	v_exp_f32_e32 v77, v77
	s_nop 0
	v_add_f32_e32 v77, 1.0, v77
	v_rcp_f32_e32 v81, v77
	s_nop 0
	v_pk_mul_f32 v[80:81], v[82:83], v[80:81]
	s_nop 0
	v_pk_mul_f32 v[78:79], v[80:81], v[78:79]
	s_nop 0
	v_cvt_pk_bf16_f32 v77, v78, v79
	v_mul_f32_e32 v78, 0xbfb8aa3b, v72
	v_mul_f32_e32 v79, 0xbfb8aa3b, v73
	v_exp_f32_e32 v78, v78
	v_exp_f32_e32 v79, v79
	v_add_f32_e32 v78, 1.0, v78
	v_add_f32_e32 v79, 1.0, v79
	v_rcp_f32_e32 v78, v78
	v_rcp_f32_e32 v79, v79
	s_nop 0
	v_pk_mul_f32 v[72:73], v[72:73], v[78:79]
	s_nop 0
	v_pk_mul_f32 v[68:69], v[72:73], v[68:69]
	v_mul_f32_e32 v73, 0xbfb8aa3b, v65
	v_cvt_pk_bf16_f32 v78, v68, v69
	v_mul_f32_e32 v68, 0xbfb8aa3b, v74
	v_mul_f32_e32 v69, 0xbfb8aa3b, v75
	v_exp_f32_e32 v68, v68
	v_exp_f32_e32 v69, v69
	v_exp_f32_e32 v73, v73
	v_add_f32_e32 v68, 1.0, v68
	v_add_f32_e32 v69, 1.0, v69
	v_rcp_f32_e32 v68, v68
	v_rcp_f32_e32 v69, v69
	v_add_f32_e32 v73, 1.0, v73
	v_rcp_f32_e32 v73, v73
	v_pk_mul_f32 v[68:69], v[74:75], v[68:69]
	s_nop 0
	v_pk_mul_f32 v[68:69], v[68:69], v[70:71]
	v_add_u32_e32 v70, 0x80, v145
	v_lshlrev_b32_e32 v71, 6, v70
	v_lshlrev_b32_e32 v72, 2, v70
	v_and_or_b32 v71, v71, s15, v142
	v_and_b32_e32 v72, 32, v72
	v_bitop3_b32 v132, v71, s65, v72 bitop3:0xde
	v_mul_f32_e32 v72, 0xbfb8aa3b, v64
	v_exp_f32_e32 v72, v72
	v_cvt_pk_bf16_f32 v79, v68, v69
	v_lshrrev_b32_e32 v68, 8, v70
	v_mov_b32_e32 v69, s4
	v_add_f32_e32 v72, 1.0, v72
	v_rcp_f32_e32 v72, v72
	s_movk_i32 s4, 0x58
	v_mad_i32_i24 v68, v68, s4, v69
	v_ashrrev_i32_e32 v69, 31, v68
	v_pk_mul_f32 v[64:65], v[64:65], v[72:73]
	v_lshlrev_b64 v[68:69], 15, v[68:69]
	v_pk_mul_f32 v[60:61], v[64:65], v[60:61]
	v_lshlrev_b32_e32 v70, 7, v70
	v_cvt_pk_bf16_f32 v60, v60, v61
	v_mul_f32_e32 v61, 0xbfb8aa3b, v66
	v_exp_f32_e32 v61, v61
	v_lshl_add_u64 v[68:69], s[16:17], 0, v[68:69]
	v_and_b32_e32 v70, 0x4000, v70
	v_mov_b32_e32 v71, v133
	v_add_f32_e32 v61, 1.0, v61
	v_rcp_f32_e32 v64, v61
	v_mul_f32_e32 v61, 0xbfb8aa3b, v67
	v_exp_f32_e32 v61, v61
	v_lshl_add_u64 v[70:71], v[68:69], 0, v[70:71]
	v_lshl_add_u64 v[70:71], v[70:71], 0, v[132:133]
	s_mov_b64 s[4:5], s[48:49]
	v_add_f32_e32 v61, 1.0, v61
	v_rcp_f32_e32 v65, v61
	global_store_dwordx4 v86, v[76:79], s[50:51]
	v_pk_mul_f32 v[64:65], v[66:67], v[64:65]
	s_nop 0
	v_pk_mul_f32 v[62:63], v[64:65], v[62:63]
	s_nop 0
	v_cvt_pk_bf16_f32 v61, v62, v63
	v_mul_f32_e32 v62, 0xbfb8aa3b, v56
	v_mul_f32_e32 v63, 0xbfb8aa3b, v57
	v_exp_f32_e32 v62, v62
	v_exp_f32_e32 v63, v63
	v_add_f32_e32 v62, 1.0, v62
	v_add_f32_e32 v63, 1.0, v63
	v_rcp_f32_e32 v62, v62
	v_rcp_f32_e32 v63, v63
	s_nop 0
	v_pk_mul_f32 v[56:57], v[56:57], v[62:63]
	s_nop 0
	v_pk_mul_f32 v[52:53], v[56:57], v[52:53]
	s_nop 0
	v_cvt_pk_bf16_f32 v62, v52, v53
	v_mul_f32_e32 v52, 0xbfb8aa3b, v58
	v_mul_f32_e32 v53, 0xbfb8aa3b, v59
	v_exp_f32_e32 v52, v52
	v_exp_f32_e32 v53, v53
	v_add_f32_e32 v52, 1.0, v52
	v_add_f32_e32 v53, 1.0, v53
	v_rcp_f32_e32 v52, v52
; __device__ __forceinline__ unsigned cvt_pk_bf16(float lo, float hi) { f32x2 v = {lo, hi}; bf16x2v b = __builtin_convertvector(v, bf16x2v); return __builtin_bit_cast(unsigned, b); }
; __device__ __forceinline__ float silu_f(float x) { return x * __builtin_amdgcn_rcpf(1.f + __expf(-x)); }
; #define PG8_WAIT_V(n) asm volatile("s_waitcnt vmcnt(" #n ")" ::: "memory")
; #define PG8_BAR __builtin_amdgcn_s_barrier()
;     __device__ __forceinline__ void operator()(const f32x4 (&acc)[2][2][4][2], const Unit& u, int wr, int wc, int fr, int fq) const {
;         const int row0 = u.pm * BM + wr * 64 + fr, col0 = u.pn * 128 + wc * 32 + 8 * fq;
; #pragma unroll
;         for (int ai = 0; ai < 2; ++ai)
; #pragma unroll
;             for (int m = 0; m < 4; ++m) {
;                 bf16_t* rowp = O + img_off(row0 + ai * HALF + m * 16, col0, D_FF / 64);
;                 const f32x4 g0 = acc[ai][0][m][0], g1 = acc[ai][0][m][1], u0 = acc[ai][1][m][0], u1 = acc[ai][1][m][1];
;                 u32x4 w;
;                 w.x = cvt_pk_bf16(silu_f(g0[0]) * u0[0], silu_f(g0[1]) * u0[1]); w.y = cvt_pk_bf16(silu_f(g0[2]) * u0[2], silu_f(g0[3]) * u0[3]);
;                 w.z = cvt_pk_bf16(silu_f(g1[0]) * u1[0], silu_f(g1[1]) * u1[1]); w.w = cvt_pk_bf16(silu_f(g1[2]) * u1[2], silu_f(g1[3]) * u1[3]);
;                 *(u32x4*)rowp = w;
; template <class Epi, class Sched, int LD>
; __device__ __forceinline__ void gemm_phase(LAS unsigned char* lds, const Gemm g, const Sched& S, const Epi& E) {
;     ...
;         if (!has_next) break;
; #pragma unroll
;         for (int a = 0; a < 2; ++a)
; #pragma unroll
;             for (int b = 0; b < 2; ++b)
; #pragma unroll
;                 for (int m = 0; m < 4; ++m)
; #pragma unroll
;                     for (int n = 0; n < 2; ++n) acc[a][b][m][n] = (f32x4){0.f, 0.f, 0.f, 0.f};
;         cur = nxt; cA = nA; cB = nB; ++ui;
;     }
;     PG8_WAIT_V(0);
;     if (wr == 0) PG8_BAR;
	v_rcp_f32_e32 v53, v53
	s_nop 0
	v_pk_mul_f32 v[52:53], v[58:59], v[52:53]
	s_nop 0
	v_pk_mul_f32 v[52:53], v[52:53], v[54:55]
	s_nop 0
	v_cvt_pk_bf16_f32 v63, v52, v53
	v_add_u32_e32 v52, 0x90, v145
	v_lshrrev_b32_e32 v54, 3, v52
	v_lshlrev_b32_e32 v53, 6, v52
	v_and_or_b32 v54, v54, 10, s64
	v_lshlrev_b32_e32 v55, 2, v52
	v_and_or_b32 v53, v53, s15, v142
	v_lshlrev_b32_e32 v54, 10, v54
	v_and_b32_e32 v55, 32, v55
	v_bitop3_b32 v132, v53, v54, v55 bitop3:0xde
	v_mul_f32_e32 v54, 0xbfb8aa3b, v48
	v_mul_f32_e32 v55, 0xbfb8aa3b, v49
	v_exp_f32_e32 v54, v54
	v_exp_f32_e32 v55, v55
	v_lshlrev_b32_e32 v52, 7, v52
	v_and_b32_e32 v52, 0x4000, v52
	v_add_f32_e32 v54, 1.0, v54
	v_add_f32_e32 v55, 1.0, v55
	v_rcp_f32_e32 v54, v54
	v_rcp_f32_e32 v55, v55
	v_mov_b32_e32 v53, v133
	v_lshl_add_u64 v[52:53], v[68:69], 0, v[52:53]
	v_lshl_add_u64 v[52:53], v[52:53], 0, v[132:133]
	v_pk_mul_f32 v[48:49], v[48:49], v[54:55]
	global_store_dwordx4 v[70:71], v[60:63], off
	v_pk_mul_f32 v[44:45], v[48:49], v[44:45]
	s_nop 0
	v_cvt_pk_bf16_f32 v44, v44, v45
	v_mul_f32_e32 v45, 0xbfb8aa3b, v50
	v_exp_f32_e32 v45, v45
	s_nop 0
	v_add_f32_e32 v45, 1.0, v45
	v_rcp_f32_e32 v48, v45
	v_mul_f32_e32 v45, 0xbfb8aa3b, v51
	v_exp_f32_e32 v45, v45
	s_nop 0
	v_add_f32_e32 v45, 1.0, v45
	v_rcp_f32_e32 v49, v45
	s_nop 0
	v_pk_mul_f32 v[48:49], v[50:51], v[48:49]
	s_nop 0
	v_pk_mul_f32 v[46:47], v[48:49], v[46:47]
	s_nop 0
	v_cvt_pk_bf16_f32 v45, v46, v47
	v_mul_f32_e32 v46, 0xbfb8aa3b, v40
	v_mul_f32_e32 v47, 0xbfb8aa3b, v41
	v_exp_f32_e32 v46, v46
	v_exp_f32_e32 v47, v47
	v_add_f32_e32 v46, 1.0, v46
	v_add_f32_e32 v47, 1.0, v47
	v_rcp_f32_e32 v46, v46
	v_rcp_f32_e32 v47, v47
	s_nop 0
	v_pk_mul_f32 v[40:41], v[40:41], v[46:47]
	s_nop 0
	v_pk_mul_f32 v[36:37], v[40:41], v[36:37]
	s_nop 0
	v_cvt_pk_bf16_f32 v46, v36, v37
	v_mul_f32_e32 v36, 0xbfb8aa3b, v42
	v_mul_f32_e32 v37, 0xbfb8aa3b, v43
	v_exp_f32_e32 v36, v36
	v_exp_f32_e32 v37, v37
	v_add_f32_e32 v36, 1.0, v36
	v_add_f32_e32 v37, 1.0, v37
	v_rcp_f32_e32 v36, v36
	v_rcp_f32_e32 v37, v37
	s_nop 0
	v_pk_mul_f32 v[36:37], v[42:43], v[36:37]
	s_nop 0
	v_pk_mul_f32 v[36:37], v[36:37], v[38:39]
	s_nop 0
	v_cvt_pk_bf16_f32 v47, v36, v37
	v_add_u32_e32 v36, 0xa0, v145
	v_lshrrev_b32_e32 v38, 3, v36
	v_lshlrev_b32_e32 v37, 6, v36
	v_and_or_b32 v38, v38, 12, s64
	v_lshlrev_b32_e32 v39, 2, v36
	v_and_or_b32 v37, v37, s15, v142
	v_lshlrev_b32_e32 v38, 10, v38
	v_and_b32_e32 v39, 32, v39
	v_bitop3_b32 v132, v37, v38, v39 bitop3:0xde
	v_mul_f32_e32 v38, 0xbfb8aa3b, v32
	v_mul_f32_e32 v39, 0xbfb8aa3b, v33
	v_exp_f32_e32 v38, v38
	v_exp_f32_e32 v39, v39
	v_lshlrev_b32_e32 v36, 7, v36
	v_and_b32_e32 v36, 0x4000, v36
	v_add_f32_e32 v38, 1.0, v38
	v_add_f32_e32 v39, 1.0, v39
	v_rcp_f32_e32 v38, v38
	v_rcp_f32_e32 v39, v39
	v_mov_b32_e32 v37, v133
	v_lshl_add_u64 v[36:37], v[68:69], 0, v[36:37]
	v_lshl_add_u64 v[36:37], v[36:37], 0, v[132:133]
	v_pk_mul_f32 v[32:33], v[32:33], v[38:39]
	global_store_dwordx4 v[52:53], v[44:47], off
	v_pk_mul_f32 v[28:29], v[32:33], v[28:29]
	s_nop 0
	v_cvt_pk_bf16_f32 v28, v28, v29
	v_mul_f32_e32 v29, 0xbfb8aa3b, v34
	v_exp_f32_e32 v29, v29
	s_nop 0
	v_add_f32_e32 v29, 1.0, v29
	v_rcp_f32_e32 v32, v29
	v_mul_f32_e32 v29, 0xbfb8aa3b, v35
	v_exp_f32_e32 v29, v29
	s_nop 0
	v_add_f32_e32 v29, 1.0, v29
	v_rcp_f32_e32 v33, v29
	s_nop 0
	v_pk_mul_f32 v[32:33], v[34:35], v[32:33]
	s_nop 0
	v_pk_mul_f32 v[30:31], v[32:33], v[30:31]
	s_nop 0
	v_cvt_pk_bf16_f32 v29, v30, v31
	v_mul_f32_e32 v30, 0xbfb8aa3b, v24
	v_mul_f32_e32 v31, 0xbfb8aa3b, v25
	v_exp_f32_e32 v30, v30
	v_exp_f32_e32 v31, v31
	v_add_f32_e32 v30, 1.0, v30
	v_add_f32_e32 v31, 1.0, v31
	v_rcp_f32_e32 v30, v30
	v_rcp_f32_e32 v31, v31
	s_nop 0
	v_pk_mul_f32 v[24:25], v[24:25], v[30:31]
	s_nop 0
	v_pk_mul_f32 v[20:21], v[24:25], v[20:21]
	s_nop 0
	v_cvt_pk_bf16_f32 v30, v20, v21
	v_mul_f32_e32 v20, 0xbfb8aa3b, v26
	v_mul_f32_e32 v21, 0xbfb8aa3b, v27
	v_exp_f32_e32 v20, v20
	v_exp_f32_e32 v21, v21
	v_add_f32_e32 v20, 1.0, v20
	v_add_f32_e32 v21, 1.0, v21
	v_rcp_f32_e32 v20, v20
	v_rcp_f32_e32 v21, v21
	s_nop 0
	v_pk_mul_f32 v[20:21], v[26:27], v[20:21]
	s_nop 0
	v_pk_mul_f32 v[20:21], v[20:21], v[22:23]
	s_nop 0
	v_cvt_pk_bf16_f32 v31, v20, v21
	v_add_u32_e32 v20, 0xb0, v145
	v_lshrrev_b32_e32 v22, 3, v20
	v_lshlrev_b32_e32 v21, 6, v20
	v_and_or_b32 v22, v22, 14, s64
	v_lshlrev_b32_e32 v23, 2, v20
	v_and_or_b32 v21, v21, s15, v142
	v_lshlrev_b32_e32 v22, 10, v22
	v_and_b32_e32 v23, 32, v23
	v_bitop3_b32 v132, v21, v22, v23 bitop3:0xde
	v_mul_f32_e32 v22, 0xbfb8aa3b, v16
	v_mul_f32_e32 v23, 0xbfb8aa3b, v17
	v_exp_f32_e32 v22, v22
	v_exp_f32_e32 v23, v23
	v_lshlrev_b32_e32 v20, 7, v20
	v_and_b32_e32 v20, 0x4000, v20
	v_add_f32_e32 v22, 1.0, v22
	v_add_f32_e32 v23, 1.0, v23
	v_rcp_f32_e32 v22, v22
	v_rcp_f32_e32 v23, v23
	v_mov_b32_e32 v21, v133
	v_lshl_add_u64 v[20:21], v[68:69], 0, v[20:21]
	v_lshl_add_u64 v[20:21], v[20:21], 0, v[132:133]
	v_pk_mul_f32 v[16:17], v[16:17], v[22:23]
	global_store_dwordx4 v[36:37], v[28:31], off
	v_pk_mul_f32 v[12:13], v[16:17], v[12:13]
	s_nop 0
	v_cvt_pk_bf16_f32 v12, v12, v13
	v_mul_f32_e32 v13, 0xbfb8aa3b, v18
	v_exp_f32_e32 v13, v13
	s_nop 0
	v_add_f32_e32 v13, 1.0, v13
	v_rcp_f32_e32 v16, v13
	v_mul_f32_e32 v13, 0xbfb8aa3b, v19
	v_exp_f32_e32 v13, v13
	s_nop 0
	v_add_f32_e32 v13, 1.0, v13
	v_rcp_f32_e32 v17, v13
	s_nop 0
	v_pk_mul_f32 v[16:17], v[18:19], v[16:17]
	s_nop 0
	v_pk_mul_f32 v[14:15], v[16:17], v[14:15]
	s_nop 0
	v_cvt_pk_bf16_f32 v13, v14, v15
	v_mul_f32_e32 v14, 0xbfb8aa3b, v8
	v_mul_f32_e32 v15, 0xbfb8aa3b, v9
	v_exp_f32_e32 v14, v14
	v_exp_f32_e32 v15, v15
	v_add_f32_e32 v14, 1.0, v14
	v_add_f32_e32 v15, 1.0, v15
	v_rcp_f32_e32 v14, v14
	v_rcp_f32_e32 v15, v15
	s_nop 0
	v_pk_mul_f32 v[8:9], v[8:9], v[14:15]
	s_nop 0
	v_pk_mul_f32 v[4:5], v[8:9], v[4:5]
	s_nop 0
	v_cvt_pk_bf16_f32 v14, v4, v5
	v_mul_f32_e32 v4, 0xbfb8aa3b, v10
	v_mul_f32_e32 v5, 0xbfb8aa3b, v11
	v_exp_f32_e32 v4, v4
	v_exp_f32_e32 v5, v5
	v_add_f32_e32 v4, 1.0, v4
	v_add_f32_e32 v5, 1.0, v5
	v_rcp_f32_e32 v4, v4
	v_rcp_f32_e32 v5, v5
	s_nop 0
	v_pk_mul_f32 v[4:5], v[10:11], v[4:5]
	s_nop 0
	v_pk_mul_f32 v[4:5], v[4:5], v[6:7]
	s_nop 0
	v_cvt_pk_bf16_f32 v15, v4, v5
	global_store_dwordx4 v[20:21], v[12:15], off
	s_cbranch_vccz .LBB0_892
	s_waitcnt vmcnt(0)
	s_cmpk_gt_u32 s2, 0xff
	s_cbranch_scc1 .LBB0_903
	s_barrier
